# layer-0 modulate phase software-pipelined: 32 loads in flight per thread, double-buffered register sets, counted vmcnt
# speedup vs baseline: 1.0211x; 1.0054x over previous
; __device__ __forceinline__ unsigned pk2(float lo, float hi) { unsigned r; asm volatile("v_cvt_pk_bf16_f32 %0, %1, %2" : "=v"(r) : "v"(lo), "v"(hi)); return r; }
; __device__ __forceinline__ void modulate_phase(const float* X, const float* sh, const float* sc, bf16_t* H, int gtid, int gthreads) {
;     for (int idx = gtid; idx < T * 128; idx += gthreads) {
;         const int row = idx >> 7, c = (idx & 127) * 8, b = row >> 11;
;         const f32x4 x0 = *(const f32x4*)(X + (size_t)row * D + c), x1 = *(const f32x4*)(X + (size_t)row * D + c + 4);
;         const f32x4 s0 = *(const f32x4*)(sc + b * 6144 + c), s1 = *(const f32x4*)(sc + b * 6144 + c + 4);
;         const f32x4 h0 = *(const f32x4*)(sh + b * 6144 + c), h1 = *(const f32x4*)(sh + b * 6144 + c + 4);
;         const f32x4 v0 = x0 * (s0 + 1.f) + h0, v1 = x1 * (s1 + 1.f) + h1;
;         u32x4 w; w.x = pk2(v0[0], v0[1]); w.y = pk2(v0[2], v0[3]); w.z = pk2(v1[0], v1[1]); w.w = pk2(v1[2], v1[3]);
;         *(u32x4*)(H + (size_t)row * D + c) = w;
;     }
.LBB0_58:
	s_or_b64 exec, exec, s[4:5]
	s_mov_b32 s2, 0
	s_barrier
	s_mov_b32 s3, s56
	v_mbcnt_lo_u32_b32 v0, -1, s2
	v_mbcnt_hi_u32_b32 v0, -1, v0
	s_mov_b32 s2, s68
	s_lshl_b32 s2, s2, 9
	s_add_i32 s2, s2, s67
	v_add_u32_e32 v2, s2, v0
	s_mov_b32 s2, 0x800000
	s_mov_b64 s[10:11], s[0:1]
	s_mov_b64 s[12:13], s[0:1]
	v_cmp_gt_i32_e32 vcc, s2, v2
	s_and_saveexec_b64 s[4:5], vcc
	s_cbranch_execz .LBB0_61
	s_load_dwordx2 s[14:15], s[10:11], 0xf8
	s_load_dwordx2 s[6:7], s[12:13], 0x0
	v_lshlrev_b32_e32 v3, 3, v2
	s_mov_b64 s[16:17], 0
	v_mov_b32_e32 v1, 0
	s_waitcnt lgkmcnt(0)
	s_add_u32 s10, s14, 0x3300000
	s_addc_u32 s11, s15, 0
	s_add_u32 s12, s14, 0x3301000
	s_addc_u32 s13, s15, 0
	s_add_u32 s14, s14, 0x3480000
	s_addc_u32 s15, s15, 0
	s_lshl_b32 s2, s3, 9
	s_lshl_b32 s3, s3, 12
	s_mov_b32 s18, 0x7fffff
	s_cmp_eq_u32 s2, 0x20000
	s_cbranch_scc0 .LBB0_60
	v_lshrrev_b32_e32 v4, 7, v2
	v_and_b32_e32 v5, 0x7f, v2
	v_lshlrev_b32_e32 v6, 5, v5
	v_lshl_add_u32 v7, v4, 12, v6
	v_lshlrev_b32_e32 v8, 4, v5
	v_lshl_add_u32 v8, v4, 11, v8
	s_nop 0
	global_load_dwordx4 v[72:75], v6, s[12:13]
	global_load_dwordx4 v[76:79], v6, s[12:13] offset:16
	global_load_dwordx4 v[88:91], v6, s[10:11]
	global_load_dwordx4 v[92:95], v6, s[10:11] offset:16
	global_load_dwordx4 v[40:43], v7, s[6:7]
	global_load_dwordx4 v[44:47], v7, s[6:7] offset:16
	s_add_u32 s6, s6, 0x400000
	s_addc_u32 s7, s7, 0
	global_load_dwordx4 v[48:51], v7, s[6:7]
	global_load_dwordx4 v[52:55], v7, s[6:7] offset:16
	s_add_u32 s6, s6, 0x400000
	s_addc_u32 s7, s7, 0
	s_add_u32 s12, s12, 0x6000
	s_addc_u32 s13, s13, 0
	s_add_u32 s10, s10, 0x6000
	s_addc_u32 s11, s11, 0
	s_nop 1
	global_load_dwordx4 v[80:83], v6, s[12:13]
	global_load_dwordx4 v[84:87], v6, s[12:13] offset:16
	global_load_dwordx4 v[96:99], v6, s[10:11]
	global_load_dwordx4 v[100:103], v6, s[10:11] offset:16
	global_load_dwordx4 v[56:59], v7, s[6:7]
	global_load_dwordx4 v[60:63], v7, s[6:7] offset:16
	s_add_u32 s6, s6, 0x400000
	s_addc_u32 s7, s7, 0
	global_load_dwordx4 v[64:67], v7, s[6:7]
	global_load_dwordx4 v[68:71], v7, s[6:7] offset:16
	s_add_u32 s6, s6, 0x400000
	s_addc_u32 s7, s7, 0
	s_add_u32 s12, s12, 0x6000
	s_addc_u32 s13, s13, 0
	s_add_u32 s10, s10, 0x6000
	s_addc_u32 s11, s11, 0
	s_nop 1
	global_load_dwordx4 v[136:139], v6, s[12:13]
	global_load_dwordx4 v[140:143], v6, s[12:13] offset:16
	global_load_dwordx4 v[152:155], v6, s[10:11]
	global_load_dwordx4 v[156:159], v6, s[10:11] offset:16
	global_load_dwordx4 v[104:107], v7, s[6:7]
	global_load_dwordx4 v[108:111], v7, s[6:7] offset:16
	s_add_u32 s6, s6, 0x400000
	s_addc_u32 s7, s7, 0
	global_load_dwordx4 v[112:115], v7, s[6:7]
	global_load_dwordx4 v[116:119], v7, s[6:7] offset:16
	s_add_u32 s6, s6, 0x400000
	s_addc_u32 s7, s7, 0
	s_add_u32 s12, s12, 0x6000
	s_addc_u32 s13, s13, 0
	s_add_u32 s10, s10, 0x6000
	s_addc_u32 s11, s11, 0
	s_nop 1
	global_load_dwordx4 v[144:147], v6, s[12:13]
	global_load_dwordx4 v[148:151], v6, s[12:13] offset:16
	global_load_dwordx4 v[160:163], v6, s[10:11]
	global_load_dwordx4 v[164:167], v6, s[10:11] offset:16
	global_load_dwordx4 v[120:123], v7, s[6:7]
	global_load_dwordx4 v[124:127], v7, s[6:7] offset:16
	s_add_u32 s6, s6, 0x400000
	s_addc_u32 s7, s7, 0
	global_load_dwordx4 v[128:131], v7, s[6:7]
	global_load_dwordx4 v[132:135], v7, s[6:7] offset:16
	s_add_u32 s6, s6, 0x400000
	s_addc_u32 s7, s7, 0
	s_add_u32 s12, s12, 0x6000
	s_addc_u32 s13, s13, 0
	s_add_u32 s10, s10, 0x6000
	s_addc_u32 s11, s11, 0
	s_nop 1
	s_waitcnt vmcnt(16)
	v_add_f32_e32 v72, 1.0, v72
	v_add_f32_e32 v73, 1.0, v73
	v_add_f32_e32 v74, 1.0, v74
	v_add_f32_e32 v75, 1.0, v75
	v_add_f32_e32 v76, 1.0, v76
	v_add_f32_e32 v77, 1.0, v77
	v_add_f32_e32 v78, 1.0, v78
	v_add_f32_e32 v79, 1.0, v79
	v_fma_f32 v40, v40, v72, v88
	v_fma_f32 v41, v41, v73, v89
	v_fma_f32 v42, v42, v74, v90
	v_fma_f32 v43, v43, v75, v91
	v_fma_f32 v44, v44, v76, v92
	v_fma_f32 v45, v45, v77, v93
	v_fma_f32 v46, v46, v78, v94
	v_fma_f32 v47, v47, v79, v95
	v_cvt_pk_bf16_f32 v40, v40, v41
	v_cvt_pk_bf16_f32 v41, v42, v43
	v_cvt_pk_bf16_f32 v42, v44, v45
	v_cvt_pk_bf16_f32 v43, v46, v47
	global_store_dwordx4 v8, v[40:43], s[14:15]
	s_add_u32 s14, s14, 0x200000
	s_addc_u32 s15, s15, 0
	v_fma_f32 v48, v48, v72, v88
	v_fma_f32 v49, v49, v73, v89
	v_fma_f32 v50, v50, v74, v90
	v_fma_f32 v51, v51, v75, v91
	v_fma_f32 v52, v52, v76, v92
	v_fma_f32 v53, v53, v77, v93
	v_fma_f32 v54, v54, v78, v94
	v_fma_f32 v55, v55, v79, v95
	v_cvt_pk_bf16_f32 v48, v48, v49
	v_cvt_pk_bf16_f32 v49, v50, v51
	v_cvt_pk_bf16_f32 v50, v52, v53
	v_cvt_pk_bf16_f32 v51, v54, v55
	global_store_dwordx4 v8, v[48:51], s[14:15]
	s_add_u32 s14, s14, 0x200000
	s_addc_u32 s15, s15, 0
	v_add_f32_e32 v80, 1.0, v80
	v_add_f32_e32 v81, 1.0, v81
	v_add_f32_e32 v82, 1.0, v82
	v_add_f32_e32 v83, 1.0, v83
	v_add_f32_e32 v84, 1.0, v84
	v_add_f32_e32 v85, 1.0, v85
	v_add_f32_e32 v86, 1.0, v86
	v_add_f32_e32 v87, 1.0, v87
	v_fma_f32 v56, v56, v80, v96
	v_fma_f32 v57, v57, v81, v97
	v_fma_f32 v58, v58, v82, v98
	v_fma_f32 v59, v59, v83, v99
	v_fma_f32 v60, v60, v84, v100
	v_fma_f32 v61, v61, v85, v101
	v_fma_f32 v62, v62, v86, v102
	v_fma_f32 v63, v63, v87, v103
	v_cvt_pk_bf16_f32 v56, v56, v57
	v_cvt_pk_bf16_f32 v57, v58, v59
	v_cvt_pk_bf16_f32 v58, v60, v61
	v_cvt_pk_bf16_f32 v59, v62, v63
	global_store_dwordx4 v8, v[56:59], s[14:15]
	s_add_u32 s14, s14, 0x200000
	s_addc_u32 s15, s15, 0
	v_fma_f32 v64, v64, v80, v96
	v_fma_f32 v65, v65, v81, v97
	v_fma_f32 v66, v66, v82, v98
	v_fma_f32 v67, v67, v83, v99
	v_fma_f32 v68, v68, v84, v100
	v_fma_f32 v69, v69, v85, v101
	v_fma_f32 v70, v70, v86, v102
	v_fma_f32 v71, v71, v87, v103
	v_cvt_pk_bf16_f32 v64, v64, v65
; __device__ __forceinline__ unsigned pk2(float lo, float hi) { unsigned r; asm volatile("v_cvt_pk_bf16_f32 %0, %1, %2" : "=v"(r) : "v"(lo), "v"(hi)); return r; }
; __device__ __forceinline__ void modulate_phase(const float* X, const float* sh, const float* sc, bf16_t* H, int gtid, int gthreads) {
;     for (int idx = gtid; idx < T * 128; idx += gthreads) {
;         const int row = idx >> 7, c = (idx & 127) * 8, b = row >> 11;
;         const f32x4 x0 = *(const f32x4*)(X + (size_t)row * D + c), x1 = *(const f32x4*)(X + (size_t)row * D + c + 4);
;         const f32x4 s0 = *(const f32x4*)(sc + b * 6144 + c), s1 = *(const f32x4*)(sc + b * 6144 + c + 4);
;         const f32x4 h0 = *(const f32x4*)(sh + b * 6144 + c), h1 = *(const f32x4*)(sh + b * 6144 + c + 4);
;         const f32x4 v0 = x0 * (s0 + 1.f) + h0, v1 = x1 * (s1 + 1.f) + h1;
;         u32x4 w; w.x = pk2(v0[0], v0[1]); w.y = pk2(v0[2], v0[3]); w.z = pk2(v1[0], v1[1]); w.w = pk2(v1[2], v1[3]);
;         *(u32x4*)(H + (size_t)row * D + c) = w;
;     }
	v_cvt_pk_bf16_f32 v65, v66, v67
	v_cvt_pk_bf16_f32 v66, v68, v69
	v_cvt_pk_bf16_f32 v67, v70, v71
	global_store_dwordx4 v8, v[64:67], s[14:15]
	s_add_u32 s14, s14, 0x200000
	s_addc_u32 s15, s15, 0
	global_load_dwordx4 v[72:75], v6, s[12:13]
	global_load_dwordx4 v[76:79], v6, s[12:13] offset:16
	global_load_dwordx4 v[88:91], v6, s[10:11]
	global_load_dwordx4 v[92:95], v6, s[10:11] offset:16
	global_load_dwordx4 v[40:43], v7, s[6:7]
	global_load_dwordx4 v[44:47], v7, s[6:7] offset:16
	s_add_u32 s6, s6, 0x400000
	s_addc_u32 s7, s7, 0
	global_load_dwordx4 v[48:51], v7, s[6:7]
	global_load_dwordx4 v[52:55], v7, s[6:7] offset:16
	s_add_u32 s6, s6, 0x400000
	s_addc_u32 s7, s7, 0
	s_add_u32 s12, s12, 0x6000
	s_addc_u32 s13, s13, 0
	s_add_u32 s10, s10, 0x6000
	s_addc_u32 s11, s11, 0
	s_nop 1
	global_load_dwordx4 v[80:83], v6, s[12:13]
	global_load_dwordx4 v[84:87], v6, s[12:13] offset:16
	global_load_dwordx4 v[96:99], v6, s[10:11]
	global_load_dwordx4 v[100:103], v6, s[10:11] offset:16
	global_load_dwordx4 v[56:59], v7, s[6:7]
	global_load_dwordx4 v[60:63], v7, s[6:7] offset:16
	s_add_u32 s6, s6, 0x400000
	s_addc_u32 s7, s7, 0
	global_load_dwordx4 v[64:67], v7, s[6:7]
	global_load_dwordx4 v[68:71], v7, s[6:7] offset:16
	s_add_u32 s6, s6, 0x400000
	s_addc_u32 s7, s7, 0
	s_add_u32 s12, s12, 0x6000
	s_addc_u32 s13, s13, 0
	s_add_u32 s10, s10, 0x6000
	s_addc_u32 s11, s11, 0
	s_nop 1
	s_waitcnt vmcnt(20)
	v_add_f32_e32 v136, 1.0, v136
	v_add_f32_e32 v137, 1.0, v137
	v_add_f32_e32 v138, 1.0, v138
	v_add_f32_e32 v139, 1.0, v139
	v_add_f32_e32 v140, 1.0, v140
	v_add_f32_e32 v141, 1.0, v141
	v_add_f32_e32 v142, 1.0, v142
	v_add_f32_e32 v143, 1.0, v143
	v_fma_f32 v104, v104, v136, v152
	v_fma_f32 v105, v105, v137, v153
	v_fma_f32 v106, v106, v138, v154
	v_fma_f32 v107, v107, v139, v155
	v_fma_f32 v108, v108, v140, v156
	v_fma_f32 v109, v109, v141, v157
	v_fma_f32 v110, v110, v142, v158
	v_fma_f32 v111, v111, v143, v159
	v_cvt_pk_bf16_f32 v104, v104, v105
	v_cvt_pk_bf16_f32 v105, v106, v107
	v_cvt_pk_bf16_f32 v106, v108, v109
	v_cvt_pk_bf16_f32 v107, v110, v111
	global_store_dwordx4 v8, v[104:107], s[14:15]
	s_add_u32 s14, s14, 0x200000
	s_addc_u32 s15, s15, 0
	v_fma_f32 v112, v112, v136, v152
	v_fma_f32 v113, v113, v137, v153
	v_fma_f32 v114, v114, v138, v154
	v_fma_f32 v115, v115, v139, v155
	v_fma_f32 v116, v116, v140, v156
	v_fma_f32 v117, v117, v141, v157
	v_fma_f32 v118, v118, v142, v158
	v_fma_f32 v119, v119, v143, v159
	v_cvt_pk_bf16_f32 v112, v112, v113
	v_cvt_pk_bf16_f32 v113, v114, v115
	v_cvt_pk_bf16_f32 v114, v116, v117
	v_cvt_pk_bf16_f32 v115, v118, v119
	global_store_dwordx4 v8, v[112:115], s[14:15]
	s_add_u32 s14, s14, 0x200000
	s_addc_u32 s15, s15, 0
	v_add_f32_e32 v144, 1.0, v144
	v_add_f32_e32 v145, 1.0, v145
	v_add_f32_e32 v146, 1.0, v146
	v_add_f32_e32 v147, 1.0, v147
	v_add_f32_e32 v148, 1.0, v148
	v_add_f32_e32 v149, 1.0, v149
	v_add_f32_e32 v150, 1.0, v150
	v_add_f32_e32 v151, 1.0, v151
	v_fma_f32 v120, v120, v144, v160
	v_fma_f32 v121, v121, v145, v161
	v_fma_f32 v122, v122, v146, v162
	v_fma_f32 v123, v123, v147, v163
	v_fma_f32 v124, v124, v148, v164
	v_fma_f32 v125, v125, v149, v165
	v_fma_f32 v126, v126, v150, v166
	v_fma_f32 v127, v127, v151, v167
	v_cvt_pk_bf16_f32 v120, v120, v121
	v_cvt_pk_bf16_f32 v121, v122, v123
	v_cvt_pk_bf16_f32 v122, v124, v125
	v_cvt_pk_bf16_f32 v123, v126, v127
	global_store_dwordx4 v8, v[120:123], s[14:15]
	s_add_u32 s14, s14, 0x200000
	s_addc_u32 s15, s15, 0
	v_fma_f32 v128, v128, v144, v160
	v_fma_f32 v129, v129, v145, v161
	v_fma_f32 v130, v130, v146, v162
	v_fma_f32 v131, v131, v147, v163
	v_fma_f32 v132, v132, v148, v164
	v_fma_f32 v133, v133, v149, v165
	v_fma_f32 v134, v134, v150, v166
	v_fma_f32 v135, v135, v151, v167
	v_cvt_pk_bf16_f32 v128, v128, v129
	v_cvt_pk_bf16_f32 v129, v130, v131
	v_cvt_pk_bf16_f32 v130, v132, v133
	v_cvt_pk_bf16_f32 v131, v134, v135
	global_store_dwordx4 v8, v[128:131], s[14:15]
	s_add_u32 s14, s14, 0x200000
	s_addc_u32 s15, s15, 0
	global_load_dwordx4 v[136:139], v6, s[12:13]
	global_load_dwordx4 v[140:143], v6, s[12:13] offset:16
	global_load_dwordx4 v[152:155], v6, s[10:11]
	global_load_dwordx4 v[156:159], v6, s[10:11] offset:16
	global_load_dwordx4 v[104:107], v7, s[6:7]
	global_load_dwordx4 v[108:111], v7, s[6:7] offset:16
	s_add_u32 s6, s6, 0x400000
	s_addc_u32 s7, s7, 0
	global_load_dwordx4 v[112:115], v7, s[6:7]
	global_load_dwordx4 v[116:119], v7, s[6:7] offset:16
	s_add_u32 s6, s6, 0x400000
	s_addc_u32 s7, s7, 0
	s_add_u32 s12, s12, 0x6000
	s_addc_u32 s13, s13, 0
	s_add_u32 s10, s10, 0x6000
	s_addc_u32 s11, s11, 0
	s_nop 1
	global_load_dwordx4 v[144:147], v6, s[12:13]
	global_load_dwordx4 v[148:151], v6, s[12:13] offset:16
	global_load_dwordx4 v[160:163], v6, s[10:11]
	global_load_dwordx4 v[164:167], v6, s[10:11] offset:16
	global_load_dwordx4 v[120:123], v7, s[6:7]
	global_load_dwordx4 v[124:127], v7, s[6:7] offset:16
	s_add_u32 s6, s6, 0x400000
	s_addc_u32 s7, s7, 0
	global_load_dwordx4 v[128:131], v7, s[6:7]
	global_load_dwordx4 v[132:135], v7, s[6:7] offset:16
	s_add_u32 s6, s6, 0x400000
	s_addc_u32 s7, s7, 0
	s_add_u32 s12, s12, 0x6000
	s_addc_u32 s13, s13, 0
	s_add_u32 s10, s10, 0x6000
	s_addc_u32 s11, s11, 0
	s_nop 1
	s_waitcnt vmcnt(20)
; __device__ __forceinline__ unsigned pk2(float lo, float hi) { unsigned r; asm volatile("v_cvt_pk_bf16_f32 %0, %1, %2" : "=v"(r) : "v"(lo), "v"(hi)); return r; }
; __device__ __forceinline__ void modulate_phase(const float* X, const float* sh, const float* sc, bf16_t* H, int gtid, int gthreads) {
;     for (int idx = gtid; idx < T * 128; idx += gthreads) {
;         const int row = idx >> 7, c = (idx & 127) * 8, b = row >> 11;
;         const f32x4 x0 = *(const f32x4*)(X + (size_t)row * D + c), x1 = *(const f32x4*)(X + (size_t)row * D + c + 4);
;         const f32x4 s0 = *(const f32x4*)(sc + b * 6144 + c), s1 = *(const f32x4*)(sc + b * 6144 + c + 4);
;         const f32x4 h0 = *(const f32x4*)(sh + b * 6144 + c), h1 = *(const f32x4*)(sh + b * 6144 + c + 4);
;         const f32x4 v0 = x0 * (s0 + 1.f) + h0, v1 = x1 * (s1 + 1.f) + h1;
;         u32x4 w; w.x = pk2(v0[0], v0[1]); w.y = pk2(v0[2], v0[3]); w.z = pk2(v1[0], v1[1]); w.w = pk2(v1[2], v1[3]);
;         *(u32x4*)(H + (size_t)row * D + c) = w;
	v_add_f32_e32 v72, 1.0, v72
	v_add_f32_e32 v73, 1.0, v73
	v_add_f32_e32 v74, 1.0, v74
	v_add_f32_e32 v75, 1.0, v75
	v_add_f32_e32 v76, 1.0, v76
	v_add_f32_e32 v77, 1.0, v77
	v_add_f32_e32 v78, 1.0, v78
	v_add_f32_e32 v79, 1.0, v79
	v_fma_f32 v40, v40, v72, v88
	v_fma_f32 v41, v41, v73, v89
	v_fma_f32 v42, v42, v74, v90
	v_fma_f32 v43, v43, v75, v91
	v_fma_f32 v44, v44, v76, v92
	v_fma_f32 v45, v45, v77, v93
	v_fma_f32 v46, v46, v78, v94
	v_fma_f32 v47, v47, v79, v95
	v_cvt_pk_bf16_f32 v40, v40, v41
	v_cvt_pk_bf16_f32 v41, v42, v43
	v_cvt_pk_bf16_f32 v42, v44, v45
	v_cvt_pk_bf16_f32 v43, v46, v47
	global_store_dwordx4 v8, v[40:43], s[14:15]
	s_add_u32 s14, s14, 0x200000
	s_addc_u32 s15, s15, 0
	v_fma_f32 v48, v48, v72, v88
	v_fma_f32 v49, v49, v73, v89
	v_fma_f32 v50, v50, v74, v90
	v_fma_f32 v51, v51, v75, v91
	v_fma_f32 v52, v52, v76, v92
	v_fma_f32 v53, v53, v77, v93
	v_fma_f32 v54, v54, v78, v94
	v_fma_f32 v55, v55, v79, v95
	v_cvt_pk_bf16_f32 v48, v48, v49
	v_cvt_pk_bf16_f32 v49, v50, v51
	v_cvt_pk_bf16_f32 v50, v52, v53
	v_cvt_pk_bf16_f32 v51, v54, v55
	global_store_dwordx4 v8, v[48:51], s[14:15]
	s_add_u32 s14, s14, 0x200000
	s_addc_u32 s15, s15, 0
	v_add_f32_e32 v80, 1.0, v80
	v_add_f32_e32 v81, 1.0, v81
	v_add_f32_e32 v82, 1.0, v82
	v_add_f32_e32 v83, 1.0, v83
	v_add_f32_e32 v84, 1.0, v84
	v_add_f32_e32 v85, 1.0, v85
	v_add_f32_e32 v86, 1.0, v86
	v_add_f32_e32 v87, 1.0, v87
	v_fma_f32 v56, v56, v80, v96
	v_fma_f32 v57, v57, v81, v97
	v_fma_f32 v58, v58, v82, v98
	v_fma_f32 v59, v59, v83, v99
	v_fma_f32 v60, v60, v84, v100
	v_fma_f32 v61, v61, v85, v101
	v_fma_f32 v62, v62, v86, v102
	v_fma_f32 v63, v63, v87, v103
	v_cvt_pk_bf16_f32 v56, v56, v57
	v_cvt_pk_bf16_f32 v57, v58, v59
	v_cvt_pk_bf16_f32 v58, v60, v61
	v_cvt_pk_bf16_f32 v59, v62, v63
	global_store_dwordx4 v8, v[56:59], s[14:15]
	s_add_u32 s14, s14, 0x200000
	s_addc_u32 s15, s15, 0
	v_fma_f32 v64, v64, v80, v96
	v_fma_f32 v65, v65, v81, v97
	v_fma_f32 v66, v66, v82, v98
	v_fma_f32 v67, v67, v83, v99
	v_fma_f32 v68, v68, v84, v100
	v_fma_f32 v69, v69, v85, v101
	v_fma_f32 v70, v70, v86, v102
	v_fma_f32 v71, v71, v87, v103
	v_cvt_pk_bf16_f32 v64, v64, v65
	v_cvt_pk_bf16_f32 v65, v66, v67
	v_cvt_pk_bf16_f32 v66, v68, v69
	v_cvt_pk_bf16_f32 v67, v70, v71
	global_store_dwordx4 v8, v[64:67], s[14:15]
	s_add_u32 s14, s14, 0x200000
	s_addc_u32 s15, s15, 0
	global_load_dwordx4 v[72:75], v6, s[12:13]
	global_load_dwordx4 v[76:79], v6, s[12:13] offset:16
	global_load_dwordx4 v[88:91], v6, s[10:11]
	global_load_dwordx4 v[92:95], v6, s[10:11] offset:16
	global_load_dwordx4 v[40:43], v7, s[6:7]
	global_load_dwordx4 v[44:47], v7, s[6:7] offset:16
	s_add_u32 s6, s6, 0x400000
	s_addc_u32 s7, s7, 0
	global_load_dwordx4 v[48:51], v7, s[6:7]
	global_load_dwordx4 v[52:55], v7, s[6:7] offset:16
	s_add_u32 s6, s6, 0x400000
	s_addc_u32 s7, s7, 0
	s_add_u32 s12, s12, 0x6000
	s_addc_u32 s13, s13, 0
	s_add_u32 s10, s10, 0x6000
	s_addc_u32 s11, s11, 0
	s_nop 1
	global_load_dwordx4 v[80:83], v6, s[12:13]
	global_load_dwordx4 v[84:87], v6, s[12:13] offset:16
	global_load_dwordx4 v[96:99], v6, s[10:11]
	global_load_dwordx4 v[100:103], v6, s[10:11] offset:16
	global_load_dwordx4 v[56:59], v7, s[6:7]
	global_load_dwordx4 v[60:63], v7, s[6:7] offset:16
	s_add_u32 s6, s6, 0x400000
	s_addc_u32 s7, s7, 0
	global_load_dwordx4 v[64:67], v7, s[6:7]
	global_load_dwordx4 v[68:71], v7, s[6:7] offset:16
	s_add_u32 s6, s6, 0x400000
	s_addc_u32 s7, s7, 0
	s_add_u32 s12, s12, 0x6000
	s_addc_u32 s13, s13, 0
	s_add_u32 s10, s10, 0x6000
	s_addc_u32 s11, s11, 0
	s_nop 1
	s_waitcnt vmcnt(20)
	v_add_f32_e32 v136, 1.0, v136
	v_add_f32_e32 v137, 1.0, v137
	v_add_f32_e32 v138, 1.0, v138
	v_add_f32_e32 v139, 1.0, v139
	v_add_f32_e32 v140, 1.0, v140
	v_add_f32_e32 v141, 1.0, v141
	v_add_f32_e32 v142, 1.0, v142
	v_add_f32_e32 v143, 1.0, v143
	v_fma_f32 v104, v104, v136, v152
	v_fma_f32 v105, v105, v137, v153
	v_fma_f32 v106, v106, v138, v154
	v_fma_f32 v107, v107, v139, v155
	v_fma_f32 v108, v108, v140, v156
	v_fma_f32 v109, v109, v141, v157
	v_fma_f32 v110, v110, v142, v158
	v_fma_f32 v111, v111, v143, v159
	v_cvt_pk_bf16_f32 v104, v104, v105
	v_cvt_pk_bf16_f32 v105, v106, v107
	v_cvt_pk_bf16_f32 v106, v108, v109
	v_cvt_pk_bf16_f32 v107, v110, v111
	global_store_dwordx4 v8, v[104:107], s[14:15]
	s_add_u32 s14, s14, 0x200000
	s_addc_u32 s15, s15, 0
	v_fma_f32 v112, v112, v136, v152
	v_fma_f32 v113, v113, v137, v153
	v_fma_f32 v114, v114, v138, v154
	v_fma_f32 v115, v115, v139, v155
	v_fma_f32 v116, v116, v140, v156
	v_fma_f32 v117, v117, v141, v157
	v_fma_f32 v118, v118, v142, v158
	v_fma_f32 v119, v119, v143, v159
	v_cvt_pk_bf16_f32 v112, v112, v113
	v_cvt_pk_bf16_f32 v113, v114, v115
	v_cvt_pk_bf16_f32 v114, v116, v117
	v_cvt_pk_bf16_f32 v115, v118, v119
	global_store_dwordx4 v8, v[112:115], s[14:15]
	s_add_u32 s14, s14, 0x200000
	s_addc_u32 s15, s15, 0
	v_add_f32_e32 v144, 1.0, v144
	v_add_f32_e32 v145, 1.0, v145
	v_add_f32_e32 v146, 1.0, v146
	v_add_f32_e32 v147, 1.0, v147
	v_add_f32_e32 v148, 1.0, v148
	v_add_f32_e32 v149, 1.0, v149
	v_add_f32_e32 v150, 1.0, v150
	v_add_f32_e32 v151, 1.0, v151
	v_fma_f32 v120, v120, v144, v160
	v_fma_f32 v121, v121, v145, v161
	v_fma_f32 v122, v122, v146, v162
	v_fma_f32 v123, v123, v147, v163
	v_fma_f32 v124, v124, v148, v164
	v_fma_f32 v125, v125, v149, v165
	v_fma_f32 v126, v126, v150, v166
	v_fma_f32 v127, v127, v151, v167
	v_cvt_pk_bf16_f32 v120, v120, v121
	v_cvt_pk_bf16_f32 v121, v122, v123
	v_cvt_pk_bf16_f32 v122, v124, v125
	v_cvt_pk_bf16_f32 v123, v126, v127
	global_store_dwordx4 v8, v[120:123], s[14:15]
	s_add_u32 s14, s14, 0x200000
	s_addc_u32 s15, s15, 0
	v_fma_f32 v128, v128, v144, v160
; __device__ __forceinline__ unsigned pk2(float lo, float hi) { unsigned r; asm volatile("v_cvt_pk_bf16_f32 %0, %1, %2" : "=v"(r) : "v"(lo), "v"(hi)); return r; }
; __device__ __forceinline__ void modulate_phase(const float* X, const float* sh, const float* sc, bf16_t* H, int gtid, int gthreads) {
;     for (int idx = gtid; idx < T * 128; idx += gthreads) {
;         const int row = idx >> 7, c = (idx & 127) * 8, b = row >> 11;
;         const f32x4 x0 = *(const f32x4*)(X + (size_t)row * D + c), x1 = *(const f32x4*)(X + (size_t)row * D + c + 4);
;         const f32x4 s0 = *(const f32x4*)(sc + b * 6144 + c), s1 = *(const f32x4*)(sc + b * 6144 + c + 4);
;         const f32x4 h0 = *(const f32x4*)(sh + b * 6144 + c), h1 = *(const f32x4*)(sh + b * 6144 + c + 4);
;         const f32x4 v0 = x0 * (s0 + 1.f) + h0, v1 = x1 * (s1 + 1.f) + h1;
;         u32x4 w; w.x = pk2(v0[0], v0[1]); w.y = pk2(v0[2], v0[3]); w.z = pk2(v1[0], v1[1]); w.w = pk2(v1[2], v1[3]);
;         *(u32x4*)(H + (size_t)row * D + c) = w;
	v_fma_f32 v129, v129, v145, v161
	v_fma_f32 v130, v130, v146, v162
	v_fma_f32 v131, v131, v147, v163
	v_fma_f32 v132, v132, v148, v164
	v_fma_f32 v133, v133, v149, v165
	v_fma_f32 v134, v134, v150, v166
	v_fma_f32 v135, v135, v151, v167
	v_cvt_pk_bf16_f32 v128, v128, v129
	v_cvt_pk_bf16_f32 v129, v130, v131
	v_cvt_pk_bf16_f32 v130, v132, v133
	v_cvt_pk_bf16_f32 v131, v134, v135
	global_store_dwordx4 v8, v[128:131], s[14:15]
	s_add_u32 s14, s14, 0x200000
	s_addc_u32 s15, s15, 0
	global_load_dwordx4 v[136:139], v6, s[12:13]
	global_load_dwordx4 v[140:143], v6, s[12:13] offset:16
	global_load_dwordx4 v[152:155], v6, s[10:11]
	global_load_dwordx4 v[156:159], v6, s[10:11] offset:16
	global_load_dwordx4 v[104:107], v7, s[6:7]
	global_load_dwordx4 v[108:111], v7, s[6:7] offset:16
	s_add_u32 s6, s6, 0x400000
	s_addc_u32 s7, s7, 0
	global_load_dwordx4 v[112:115], v7, s[6:7]
	global_load_dwordx4 v[116:119], v7, s[6:7] offset:16
	s_add_u32 s6, s6, 0x400000
	s_addc_u32 s7, s7, 0
	s_add_u32 s12, s12, 0x6000
	s_addc_u32 s13, s13, 0
	s_add_u32 s10, s10, 0x6000
	s_addc_u32 s11, s11, 0
	s_nop 1
	global_load_dwordx4 v[144:147], v6, s[12:13]
	global_load_dwordx4 v[148:151], v6, s[12:13] offset:16
	global_load_dwordx4 v[160:163], v6, s[10:11]
	global_load_dwordx4 v[164:167], v6, s[10:11] offset:16
	global_load_dwordx4 v[120:123], v7, s[6:7]
	global_load_dwordx4 v[124:127], v7, s[6:7] offset:16
	s_add_u32 s6, s6, 0x400000
	s_addc_u32 s7, s7, 0
	global_load_dwordx4 v[128:131], v7, s[6:7]
	global_load_dwordx4 v[132:135], v7, s[6:7] offset:16
	s_add_u32 s6, s6, 0x400000
	s_addc_u32 s7, s7, 0
	s_add_u32 s12, s12, 0x6000
	s_addc_u32 s13, s13, 0
	s_add_u32 s10, s10, 0x6000
	s_addc_u32 s11, s11, 0
	s_nop 1
	s_waitcnt vmcnt(20)
	v_add_f32_e32 v72, 1.0, v72
	v_add_f32_e32 v73, 1.0, v73
	v_add_f32_e32 v74, 1.0, v74
	v_add_f32_e32 v75, 1.0, v75
	v_add_f32_e32 v76, 1.0, v76
	v_add_f32_e32 v77, 1.0, v77
	v_add_f32_e32 v78, 1.0, v78
	v_add_f32_e32 v79, 1.0, v79
	v_fma_f32 v40, v40, v72, v88
	v_fma_f32 v41, v41, v73, v89
	v_fma_f32 v42, v42, v74, v90
	v_fma_f32 v43, v43, v75, v91
	v_fma_f32 v44, v44, v76, v92
	v_fma_f32 v45, v45, v77, v93
	v_fma_f32 v46, v46, v78, v94
	v_fma_f32 v47, v47, v79, v95
	v_cvt_pk_bf16_f32 v40, v40, v41
	v_cvt_pk_bf16_f32 v41, v42, v43
	v_cvt_pk_bf16_f32 v42, v44, v45
	v_cvt_pk_bf16_f32 v43, v46, v47
	global_store_dwordx4 v8, v[40:43], s[14:15]
	s_add_u32 s14, s14, 0x200000
	s_addc_u32 s15, s15, 0
	v_fma_f32 v48, v48, v72, v88
	v_fma_f32 v49, v49, v73, v89
	v_fma_f32 v50, v50, v74, v90
	v_fma_f32 v51, v51, v75, v91
	v_fma_f32 v52, v52, v76, v92
	v_fma_f32 v53, v53, v77, v93
	v_fma_f32 v54, v54, v78, v94
	v_fma_f32 v55, v55, v79, v95
	v_cvt_pk_bf16_f32 v48, v48, v49
	v_cvt_pk_bf16_f32 v49, v50, v51
	v_cvt_pk_bf16_f32 v50, v52, v53
	v_cvt_pk_bf16_f32 v51, v54, v55
	global_store_dwordx4 v8, v[48:51], s[14:15]
	s_add_u32 s14, s14, 0x200000
	s_addc_u32 s15, s15, 0
	v_add_f32_e32 v80, 1.0, v80
	v_add_f32_e32 v81, 1.0, v81
	v_add_f32_e32 v82, 1.0, v82
	v_add_f32_e32 v83, 1.0, v83
	v_add_f32_e32 v84, 1.0, v84
	v_add_f32_e32 v85, 1.0, v85
	v_add_f32_e32 v86, 1.0, v86
	v_add_f32_e32 v87, 1.0, v87
	v_fma_f32 v56, v56, v80, v96
	v_fma_f32 v57, v57, v81, v97
	v_fma_f32 v58, v58, v82, v98
	v_fma_f32 v59, v59, v83, v99
	v_fma_f32 v60, v60, v84, v100
	v_fma_f32 v61, v61, v85, v101
	v_fma_f32 v62, v62, v86, v102
	v_fma_f32 v63, v63, v87, v103
	v_cvt_pk_bf16_f32 v56, v56, v57
	v_cvt_pk_bf16_f32 v57, v58, v59
	v_cvt_pk_bf16_f32 v58, v60, v61
	v_cvt_pk_bf16_f32 v59, v62, v63
	global_store_dwordx4 v8, v[56:59], s[14:15]
	s_add_u32 s14, s14, 0x200000
	s_addc_u32 s15, s15, 0
	v_fma_f32 v64, v64, v80, v96
	v_fma_f32 v65, v65, v81, v97
	v_fma_f32 v66, v66, v82, v98
	v_fma_f32 v67, v67, v83, v99
	v_fma_f32 v68, v68, v84, v100
	v_fma_f32 v69, v69, v85, v101
	v_fma_f32 v70, v70, v86, v102
	v_fma_f32 v71, v71, v87, v103
	v_cvt_pk_bf16_f32 v64, v64, v65
	v_cvt_pk_bf16_f32 v65, v66, v67
	v_cvt_pk_bf16_f32 v66, v68, v69
	v_cvt_pk_bf16_f32 v67, v70, v71
	global_store_dwordx4 v8, v[64:67], s[14:15]
	s_add_u32 s14, s14, 0x200000
	s_addc_u32 s15, s15, 0
	global_load_dwordx4 v[72:75], v6, s[12:13]
	global_load_dwordx4 v[76:79], v6, s[12:13] offset:16
	global_load_dwordx4 v[88:91], v6, s[10:11]
	global_load_dwordx4 v[92:95], v6, s[10:11] offset:16
	global_load_dwordx4 v[40:43], v7, s[6:7]
	global_load_dwordx4 v[44:47], v7, s[6:7] offset:16
	s_add_u32 s6, s6, 0x400000
	s_addc_u32 s7, s7, 0
	global_load_dwordx4 v[48:51], v7, s[6:7]
	global_load_dwordx4 v[52:55], v7, s[6:7] offset:16
	s_add_u32 s6, s6, 0x400000
	s_addc_u32 s7, s7, 0
	s_add_u32 s12, s12, 0x6000
	s_addc_u32 s13, s13, 0
	s_add_u32 s10, s10, 0x6000
	s_addc_u32 s11, s11, 0
	s_nop 1
	global_load_dwordx4 v[80:83], v6, s[12:13]
	global_load_dwordx4 v[84:87], v6, s[12:13] offset:16
	global_load_dwordx4 v[96:99], v6, s[10:11]
	global_load_dwordx4 v[100:103], v6, s[10:11] offset:16
	global_load_dwordx4 v[56:59], v7, s[6:7]
	global_load_dwordx4 v[60:63], v7, s[6:7] offset:16
	s_add_u32 s6, s6, 0x400000
	s_addc_u32 s7, s7, 0
	global_load_dwordx4 v[64:67], v7, s[6:7]
	global_load_dwordx4 v[68:71], v7, s[6:7] offset:16
	s_add_u32 s6, s6, 0x400000
	s_addc_u32 s7, s7, 0
	s_add_u32 s12, s12, 0x6000
	s_addc_u32 s13, s13, 0
	s_add_u32 s10, s10, 0x6000
	s_addc_u32 s11, s11, 0
	s_nop 1
	s_waitcnt vmcnt(20)
; __device__ __forceinline__ unsigned pk2(float lo, float hi) { unsigned r; asm volatile("v_cvt_pk_bf16_f32 %0, %1, %2" : "=v"(r) : "v"(lo), "v"(hi)); return r; }
; __device__ __forceinline__ void modulate_phase(const float* X, const float* sh, const float* sc, bf16_t* H, int gtid, int gthreads) {
;     for (int idx = gtid; idx < T * 128; idx += gthreads) {
;         const int row = idx >> 7, c = (idx & 127) * 8, b = row >> 11;
;         const f32x4 x0 = *(const f32x4*)(X + (size_t)row * D + c), x1 = *(const f32x4*)(X + (size_t)row * D + c + 4);
;         const f32x4 s0 = *(const f32x4*)(sc + b * 6144 + c), s1 = *(const f32x4*)(sc + b * 6144 + c + 4);
;         const f32x4 h0 = *(const f32x4*)(sh + b * 6144 + c), h1 = *(const f32x4*)(sh + b * 6144 + c + 4);
;         const f32x4 v0 = x0 * (s0 + 1.f) + h0, v1 = x1 * (s1 + 1.f) + h1;
;         u32x4 w; w.x = pk2(v0[0], v0[1]); w.y = pk2(v0[2], v0[3]); w.z = pk2(v1[0], v1[1]); w.w = pk2(v1[2], v1[3]);
;         *(u32x4*)(H + (size_t)row * D + c) = w;
	v_add_f32_e32 v136, 1.0, v136
	v_add_f32_e32 v137, 1.0, v137
	v_add_f32_e32 v138, 1.0, v138
	v_add_f32_e32 v139, 1.0, v139
	v_add_f32_e32 v140, 1.0, v140
	v_add_f32_e32 v141, 1.0, v141
	v_add_f32_e32 v142, 1.0, v142
	v_add_f32_e32 v143, 1.0, v143
	v_fma_f32 v104, v104, v136, v152
	v_fma_f32 v105, v105, v137, v153
	v_fma_f32 v106, v106, v138, v154
	v_fma_f32 v107, v107, v139, v155
	v_fma_f32 v108, v108, v140, v156
	v_fma_f32 v109, v109, v141, v157
	v_fma_f32 v110, v110, v142, v158
	v_fma_f32 v111, v111, v143, v159
	v_cvt_pk_bf16_f32 v104, v104, v105
	v_cvt_pk_bf16_f32 v105, v106, v107
	v_cvt_pk_bf16_f32 v106, v108, v109
	v_cvt_pk_bf16_f32 v107, v110, v111
	global_store_dwordx4 v8, v[104:107], s[14:15]
	s_add_u32 s14, s14, 0x200000
	s_addc_u32 s15, s15, 0
	v_fma_f32 v112, v112, v136, v152
	v_fma_f32 v113, v113, v137, v153
	v_fma_f32 v114, v114, v138, v154
	v_fma_f32 v115, v115, v139, v155
	v_fma_f32 v116, v116, v140, v156
	v_fma_f32 v117, v117, v141, v157
	v_fma_f32 v118, v118, v142, v158
	v_fma_f32 v119, v119, v143, v159
	v_cvt_pk_bf16_f32 v112, v112, v113
	v_cvt_pk_bf16_f32 v113, v114, v115
	v_cvt_pk_bf16_f32 v114, v116, v117
	v_cvt_pk_bf16_f32 v115, v118, v119
	global_store_dwordx4 v8, v[112:115], s[14:15]
	s_add_u32 s14, s14, 0x200000
	s_addc_u32 s15, s15, 0
	v_add_f32_e32 v144, 1.0, v144
	v_add_f32_e32 v145, 1.0, v145
	v_add_f32_e32 v146, 1.0, v146
	v_add_f32_e32 v147, 1.0, v147
	v_add_f32_e32 v148, 1.0, v148
	v_add_f32_e32 v149, 1.0, v149
	v_add_f32_e32 v150, 1.0, v150
	v_add_f32_e32 v151, 1.0, v151
	v_fma_f32 v120, v120, v144, v160
	v_fma_f32 v121, v121, v145, v161
	v_fma_f32 v122, v122, v146, v162
	v_fma_f32 v123, v123, v147, v163
	v_fma_f32 v124, v124, v148, v164
	v_fma_f32 v125, v125, v149, v165
	v_fma_f32 v126, v126, v150, v166
	v_fma_f32 v127, v127, v151, v167
	v_cvt_pk_bf16_f32 v120, v120, v121
	v_cvt_pk_bf16_f32 v121, v122, v123
	v_cvt_pk_bf16_f32 v122, v124, v125
	v_cvt_pk_bf16_f32 v123, v126, v127
	global_store_dwordx4 v8, v[120:123], s[14:15]
	s_add_u32 s14, s14, 0x200000
	s_addc_u32 s15, s15, 0
	v_fma_f32 v128, v128, v144, v160
	v_fma_f32 v129, v129, v145, v161
	v_fma_f32 v130, v130, v146, v162
	v_fma_f32 v131, v131, v147, v163
	v_fma_f32 v132, v132, v148, v164
	v_fma_f32 v133, v133, v149, v165
	v_fma_f32 v134, v134, v150, v166
	v_fma_f32 v135, v135, v151, v167
	v_cvt_pk_bf16_f32 v128, v128, v129
	v_cvt_pk_bf16_f32 v129, v130, v131
	v_cvt_pk_bf16_f32 v130, v132, v133
	v_cvt_pk_bf16_f32 v131, v134, v135
	global_store_dwordx4 v8, v[128:131], s[14:15]
	s_add_u32 s14, s14, 0x200000
	s_addc_u32 s15, s15, 0
	global_load_dwordx4 v[136:139], v6, s[12:13]
	global_load_dwordx4 v[140:143], v6, s[12:13] offset:16
	global_load_dwordx4 v[152:155], v6, s[10:11]
	global_load_dwordx4 v[156:159], v6, s[10:11] offset:16
	global_load_dwordx4 v[104:107], v7, s[6:7]
	global_load_dwordx4 v[108:111], v7, s[6:7] offset:16
	s_add_u32 s6, s6, 0x400000
	s_addc_u32 s7, s7, 0
	global_load_dwordx4 v[112:115], v7, s[6:7]
	global_load_dwordx4 v[116:119], v7, s[6:7] offset:16
	s_add_u32 s6, s6, 0x400000
	s_addc_u32 s7, s7, 0
	s_add_u32 s12, s12, 0x6000
	s_addc_u32 s13, s13, 0
	s_add_u32 s10, s10, 0x6000
	s_addc_u32 s11, s11, 0
	s_nop 1
	global_load_dwordx4 v[144:147], v6, s[12:13]
	global_load_dwordx4 v[148:151], v6, s[12:13] offset:16
	global_load_dwordx4 v[160:163], v6, s[10:11]
	global_load_dwordx4 v[164:167], v6, s[10:11] offset:16
	global_load_dwordx4 v[120:123], v7, s[6:7]
	global_load_dwordx4 v[124:127], v7, s[6:7] offset:16
	s_add_u32 s6, s6, 0x400000
	s_addc_u32 s7, s7, 0
	global_load_dwordx4 v[128:131], v7, s[6:7]
	global_load_dwordx4 v[132:135], v7, s[6:7] offset:16
	s_add_u32 s6, s6, 0x400000
	s_addc_u32 s7, s7, 0
	s_add_u32 s12, s12, 0x6000
	s_addc_u32 s13, s13, 0
	s_add_u32 s10, s10, 0x6000
	s_addc_u32 s11, s11, 0
	s_nop 1
	s_waitcnt vmcnt(20)
	v_add_f32_e32 v72, 1.0, v72
	v_add_f32_e32 v73, 1.0, v73
	v_add_f32_e32 v74, 1.0, v74
	v_add_f32_e32 v75, 1.0, v75
	v_add_f32_e32 v76, 1.0, v76
	v_add_f32_e32 v77, 1.0, v77
	v_add_f32_e32 v78, 1.0, v78
	v_add_f32_e32 v79, 1.0, v79
	v_fma_f32 v40, v40, v72, v88
	v_fma_f32 v41, v41, v73, v89
	v_fma_f32 v42, v42, v74, v90
	v_fma_f32 v43, v43, v75, v91
	v_fma_f32 v44, v44, v76, v92
	v_fma_f32 v45, v45, v77, v93
	v_fma_f32 v46, v46, v78, v94
	v_fma_f32 v47, v47, v79, v95
	v_cvt_pk_bf16_f32 v40, v40, v41
	v_cvt_pk_bf16_f32 v41, v42, v43
	v_cvt_pk_bf16_f32 v42, v44, v45
	v_cvt_pk_bf16_f32 v43, v46, v47
	global_store_dwordx4 v8, v[40:43], s[14:15]
	s_add_u32 s14, s14, 0x200000
	s_addc_u32 s15, s15, 0
	v_fma_f32 v48, v48, v72, v88
	v_fma_f32 v49, v49, v73, v89
	v_fma_f32 v50, v50, v74, v90
	v_fma_f32 v51, v51, v75, v91
	v_fma_f32 v52, v52, v76, v92
	v_fma_f32 v53, v53, v77, v93
	v_fma_f32 v54, v54, v78, v94
	v_fma_f32 v55, v55, v79, v95
	v_cvt_pk_bf16_f32 v48, v48, v49
	v_cvt_pk_bf16_f32 v49, v50, v51
	v_cvt_pk_bf16_f32 v50, v52, v53
	v_cvt_pk_bf16_f32 v51, v54, v55
	global_store_dwordx4 v8, v[48:51], s[14:15]
	s_add_u32 s14, s14, 0x200000
	s_addc_u32 s15, s15, 0
	v_add_f32_e32 v80, 1.0, v80
	v_add_f32_e32 v81, 1.0, v81
	v_add_f32_e32 v82, 1.0, v82
	v_add_f32_e32 v83, 1.0, v83
	v_add_f32_e32 v84, 1.0, v84
	v_add_f32_e32 v85, 1.0, v85
	v_add_f32_e32 v86, 1.0, v86
	v_add_f32_e32 v87, 1.0, v87
	v_fma_f32 v56, v56, v80, v96
	v_fma_f32 v57, v57, v81, v97
	v_fma_f32 v58, v58, v82, v98
	v_fma_f32 v59, v59, v83, v99
	v_fma_f32 v60, v60, v84, v100
	v_fma_f32 v61, v61, v85, v101
	v_fma_f32 v62, v62, v86, v102
	v_fma_f32 v63, v63, v87, v103
	v_cvt_pk_bf16_f32 v56, v56, v57
	v_cvt_pk_bf16_f32 v57, v58, v59
	v_cvt_pk_bf16_f32 v58, v60, v61
	v_cvt_pk_bf16_f32 v59, v62, v63
	global_store_dwordx4 v8, v[56:59], s[14:15]
; __device__ __forceinline__ unsigned pk2(float lo, float hi) { unsigned r; asm volatile("v_cvt_pk_bf16_f32 %0, %1, %2" : "=v"(r) : "v"(lo), "v"(hi)); return r; }
; __device__ __forceinline__ void modulate_phase(const float* X, const float* sh, const float* sc, bf16_t* H, int gtid, int gthreads) {
;     for (int idx = gtid; idx < T * 128; idx += gthreads) {
;         const int row = idx >> 7, c = (idx & 127) * 8, b = row >> 11;
;         const f32x4 x0 = *(const f32x4*)(X + (size_t)row * D + c), x1 = *(const f32x4*)(X + (size_t)row * D + c + 4);
;         const f32x4 s0 = *(const f32x4*)(sc + b * 6144 + c), s1 = *(const f32x4*)(sc + b * 6144 + c + 4);
;         const f32x4 h0 = *(const f32x4*)(sh + b * 6144 + c), h1 = *(const f32x4*)(sh + b * 6144 + c + 4);
;         const f32x4 v0 = x0 * (s0 + 1.f) + h0, v1 = x1 * (s1 + 1.f) + h1;
;         u32x4 w; w.x = pk2(v0[0], v0[1]); w.y = pk2(v0[2], v0[3]); w.z = pk2(v1[0], v1[1]); w.w = pk2(v1[2], v1[3]);
;         *(u32x4*)(H + (size_t)row * D + c) = w;
	s_add_u32 s14, s14, 0x200000
	s_addc_u32 s15, s15, 0
	v_fma_f32 v64, v64, v80, v96
	v_fma_f32 v65, v65, v81, v97
	v_fma_f32 v66, v66, v82, v98
	v_fma_f32 v67, v67, v83, v99
	v_fma_f32 v68, v68, v84, v100
	v_fma_f32 v69, v69, v85, v101
	v_fma_f32 v70, v70, v86, v102
	v_fma_f32 v71, v71, v87, v103
	v_cvt_pk_bf16_f32 v64, v64, v65
	v_cvt_pk_bf16_f32 v65, v66, v67
	v_cvt_pk_bf16_f32 v66, v68, v69
	v_cvt_pk_bf16_f32 v67, v70, v71
	global_store_dwordx4 v8, v[64:67], s[14:15]
	s_add_u32 s14, s14, 0x200000
	s_addc_u32 s15, s15, 0
	global_load_dwordx4 v[72:75], v6, s[12:13]
	global_load_dwordx4 v[76:79], v6, s[12:13] offset:16
	global_load_dwordx4 v[88:91], v6, s[10:11]
	global_load_dwordx4 v[92:95], v6, s[10:11] offset:16
	global_load_dwordx4 v[40:43], v7, s[6:7]
	global_load_dwordx4 v[44:47], v7, s[6:7] offset:16
	s_add_u32 s6, s6, 0x400000
	s_addc_u32 s7, s7, 0
	global_load_dwordx4 v[48:51], v7, s[6:7]
	global_load_dwordx4 v[52:55], v7, s[6:7] offset:16
	s_add_u32 s6, s6, 0x400000
	s_addc_u32 s7, s7, 0
	s_add_u32 s12, s12, 0x6000
	s_addc_u32 s13, s13, 0
	s_add_u32 s10, s10, 0x6000
	s_addc_u32 s11, s11, 0
	s_nop 1
	global_load_dwordx4 v[80:83], v6, s[12:13]
	global_load_dwordx4 v[84:87], v6, s[12:13] offset:16
	global_load_dwordx4 v[96:99], v6, s[10:11]
	global_load_dwordx4 v[100:103], v6, s[10:11] offset:16
	global_load_dwordx4 v[56:59], v7, s[6:7]
	global_load_dwordx4 v[60:63], v7, s[6:7] offset:16
	s_add_u32 s6, s6, 0x400000
	s_addc_u32 s7, s7, 0
	global_load_dwordx4 v[64:67], v7, s[6:7]
	global_load_dwordx4 v[68:71], v7, s[6:7] offset:16
	s_add_u32 s6, s6, 0x400000
	s_addc_u32 s7, s7, 0
	s_add_u32 s12, s12, 0x6000
	s_addc_u32 s13, s13, 0
	s_add_u32 s10, s10, 0x6000
	s_addc_u32 s11, s11, 0
	s_nop 1
	s_waitcnt vmcnt(20)
	v_add_f32_e32 v136, 1.0, v136
	v_add_f32_e32 v137, 1.0, v137
	v_add_f32_e32 v138, 1.0, v138
	v_add_f32_e32 v139, 1.0, v139
	v_add_f32_e32 v140, 1.0, v140
	v_add_f32_e32 v141, 1.0, v141
	v_add_f32_e32 v142, 1.0, v142
	v_add_f32_e32 v143, 1.0, v143
	v_fma_f32 v104, v104, v136, v152
	v_fma_f32 v105, v105, v137, v153
	v_fma_f32 v106, v106, v138, v154
	v_fma_f32 v107, v107, v139, v155
	v_fma_f32 v108, v108, v140, v156
	v_fma_f32 v109, v109, v141, v157
	v_fma_f32 v110, v110, v142, v158
	v_fma_f32 v111, v111, v143, v159
	v_cvt_pk_bf16_f32 v104, v104, v105
	v_cvt_pk_bf16_f32 v105, v106, v107
	v_cvt_pk_bf16_f32 v106, v108, v109
	v_cvt_pk_bf16_f32 v107, v110, v111
	global_store_dwordx4 v8, v[104:107], s[14:15]
	s_add_u32 s14, s14, 0x200000
	s_addc_u32 s15, s15, 0
	v_fma_f32 v112, v112, v136, v152
	v_fma_f32 v113, v113, v137, v153
	v_fma_f32 v114, v114, v138, v154
	v_fma_f32 v115, v115, v139, v155
	v_fma_f32 v116, v116, v140, v156
	v_fma_f32 v117, v117, v141, v157
	v_fma_f32 v118, v118, v142, v158
	v_fma_f32 v119, v119, v143, v159
	v_cvt_pk_bf16_f32 v112, v112, v113
	v_cvt_pk_bf16_f32 v113, v114, v115
	v_cvt_pk_bf16_f32 v114, v116, v117
	v_cvt_pk_bf16_f32 v115, v118, v119
	global_store_dwordx4 v8, v[112:115], s[14:15]
	s_add_u32 s14, s14, 0x200000
	s_addc_u32 s15, s15, 0
	v_add_f32_e32 v144, 1.0, v144
	v_add_f32_e32 v145, 1.0, v145
	v_add_f32_e32 v146, 1.0, v146
	v_add_f32_e32 v147, 1.0, v147
	v_add_f32_e32 v148, 1.0, v148
	v_add_f32_e32 v149, 1.0, v149
	v_add_f32_e32 v150, 1.0, v150
	v_add_f32_e32 v151, 1.0, v151
	v_fma_f32 v120, v120, v144, v160
	v_fma_f32 v121, v121, v145, v161
	v_fma_f32 v122, v122, v146, v162
	v_fma_f32 v123, v123, v147, v163
	v_fma_f32 v124, v124, v148, v164
	v_fma_f32 v125, v125, v149, v165
	v_fma_f32 v126, v126, v150, v166
	v_fma_f32 v127, v127, v151, v167
	v_cvt_pk_bf16_f32 v120, v120, v121
	v_cvt_pk_bf16_f32 v121, v122, v123
	v_cvt_pk_bf16_f32 v122, v124, v125
	v_cvt_pk_bf16_f32 v123, v126, v127
	global_store_dwordx4 v8, v[120:123], s[14:15]
	s_add_u32 s14, s14, 0x200000
	s_addc_u32 s15, s15, 0
	v_fma_f32 v128, v128, v144, v160
	v_fma_f32 v129, v129, v145, v161
	v_fma_f32 v130, v130, v146, v162
	v_fma_f32 v131, v131, v147, v163
	v_fma_f32 v132, v132, v148, v164
	v_fma_f32 v133, v133, v149, v165
	v_fma_f32 v134, v134, v150, v166
	v_fma_f32 v135, v135, v151, v167
	v_cvt_pk_bf16_f32 v128, v128, v129
	v_cvt_pk_bf16_f32 v129, v130, v131
	v_cvt_pk_bf16_f32 v130, v132, v133
	v_cvt_pk_bf16_f32 v131, v134, v135
	global_store_dwordx4 v8, v[128:131], s[14:15]
	s_add_u32 s14, s14, 0x200000
	s_addc_u32 s15, s15, 0
	global_load_dwordx4 v[136:139], v6, s[12:13]
	global_load_dwordx4 v[140:143], v6, s[12:13] offset:16
	global_load_dwordx4 v[152:155], v6, s[10:11]
	global_load_dwordx4 v[156:159], v6, s[10:11] offset:16
	global_load_dwordx4 v[104:107], v7, s[6:7]
	global_load_dwordx4 v[108:111], v7, s[6:7] offset:16
	s_add_u32 s6, s6, 0x400000
	s_addc_u32 s7, s7, 0
	global_load_dwordx4 v[112:115], v7, s[6:7]
	global_load_dwordx4 v[116:119], v7, s[6:7] offset:16
	s_add_u32 s6, s6, 0x400000
	s_addc_u32 s7, s7, 0
	s_add_u32 s12, s12, 0x6000
	s_addc_u32 s13, s13, 0
	s_add_u32 s10, s10, 0x6000
	s_addc_u32 s11, s11, 0
	s_nop 1
	global_load_dwordx4 v[144:147], v6, s[12:13]
	global_load_dwordx4 v[148:151], v6, s[12:13] offset:16
	global_load_dwordx4 v[160:163], v6, s[10:11]
	global_load_dwordx4 v[164:167], v6, s[10:11] offset:16
	global_load_dwordx4 v[120:123], v7, s[6:7]
	global_load_dwordx4 v[124:127], v7, s[6:7] offset:16
	s_add_u32 s6, s6, 0x400000
	s_addc_u32 s7, s7, 0
	global_load_dwordx4 v[128:131], v7, s[6:7]
	global_load_dwordx4 v[132:135], v7, s[6:7] offset:16
	s_add_u32 s6, s6, 0x400000
	s_addc_u32 s7, s7, 0
	s_add_u32 s12, s12, 0x6000
	s_addc_u32 s13, s13, 0
	s_add_u32 s10, s10, 0x6000
	s_addc_u32 s11, s11, 0
	s_nop 1
	s_waitcnt vmcnt(20)
; __device__ __forceinline__ unsigned pk2(float lo, float hi) { unsigned r; asm volatile("v_cvt_pk_bf16_f32 %0, %1, %2" : "=v"(r) : "v"(lo), "v"(hi)); return r; }
; __device__ __forceinline__ void modulate_phase(const float* X, const float* sh, const float* sc, bf16_t* H, int gtid, int gthreads) {
;     for (int idx = gtid; idx < T * 128; idx += gthreads) {
;         const int row = idx >> 7, c = (idx & 127) * 8, b = row >> 11;
;         const f32x4 x0 = *(const f32x4*)(X + (size_t)row * D + c), x1 = *(const f32x4*)(X + (size_t)row * D + c + 4);
;         const f32x4 s0 = *(const f32x4*)(sc + b * 6144 + c), s1 = *(const f32x4*)(sc + b * 6144 + c + 4);
;         const f32x4 h0 = *(const f32x4*)(sh + b * 6144 + c), h1 = *(const f32x4*)(sh + b * 6144 + c + 4);
;         const f32x4 v0 = x0 * (s0 + 1.f) + h0, v1 = x1 * (s1 + 1.f) + h1;
;         u32x4 w; w.x = pk2(v0[0], v0[1]); w.y = pk2(v0[2], v0[3]); w.z = pk2(v1[0], v1[1]); w.w = pk2(v1[2], v1[3]);
;         *(u32x4*)(H + (size_t)row * D + c) = w;
	v_add_f32_e32 v72, 1.0, v72
	v_add_f32_e32 v73, 1.0, v73
	v_add_f32_e32 v74, 1.0, v74
	v_add_f32_e32 v75, 1.0, v75
	v_add_f32_e32 v76, 1.0, v76
	v_add_f32_e32 v77, 1.0, v77
	v_add_f32_e32 v78, 1.0, v78
	v_add_f32_e32 v79, 1.0, v79
	v_fma_f32 v40, v40, v72, v88
	v_fma_f32 v41, v41, v73, v89
	v_fma_f32 v42, v42, v74, v90
	v_fma_f32 v43, v43, v75, v91
	v_fma_f32 v44, v44, v76, v92
	v_fma_f32 v45, v45, v77, v93
	v_fma_f32 v46, v46, v78, v94
	v_fma_f32 v47, v47, v79, v95
	v_cvt_pk_bf16_f32 v40, v40, v41
	v_cvt_pk_bf16_f32 v41, v42, v43
	v_cvt_pk_bf16_f32 v42, v44, v45
	v_cvt_pk_bf16_f32 v43, v46, v47
	global_store_dwordx4 v8, v[40:43], s[14:15]
	s_add_u32 s14, s14, 0x200000
	s_addc_u32 s15, s15, 0
	v_fma_f32 v48, v48, v72, v88
	v_fma_f32 v49, v49, v73, v89
	v_fma_f32 v50, v50, v74, v90
	v_fma_f32 v51, v51, v75, v91
	v_fma_f32 v52, v52, v76, v92
	v_fma_f32 v53, v53, v77, v93
	v_fma_f32 v54, v54, v78, v94
	v_fma_f32 v55, v55, v79, v95
	v_cvt_pk_bf16_f32 v48, v48, v49
	v_cvt_pk_bf16_f32 v49, v50, v51
	v_cvt_pk_bf16_f32 v50, v52, v53
	v_cvt_pk_bf16_f32 v51, v54, v55
	global_store_dwordx4 v8, v[48:51], s[14:15]
	s_add_u32 s14, s14, 0x200000
	s_addc_u32 s15, s15, 0
	v_add_f32_e32 v80, 1.0, v80
	v_add_f32_e32 v81, 1.0, v81
	v_add_f32_e32 v82, 1.0, v82
	v_add_f32_e32 v83, 1.0, v83
	v_add_f32_e32 v84, 1.0, v84
	v_add_f32_e32 v85, 1.0, v85
	v_add_f32_e32 v86, 1.0, v86
	v_add_f32_e32 v87, 1.0, v87
	v_fma_f32 v56, v56, v80, v96
	v_fma_f32 v57, v57, v81, v97
	v_fma_f32 v58, v58, v82, v98
	v_fma_f32 v59, v59, v83, v99
	v_fma_f32 v60, v60, v84, v100
	v_fma_f32 v61, v61, v85, v101
	v_fma_f32 v62, v62, v86, v102
	v_fma_f32 v63, v63, v87, v103
	v_cvt_pk_bf16_f32 v56, v56, v57
	v_cvt_pk_bf16_f32 v57, v58, v59
	v_cvt_pk_bf16_f32 v58, v60, v61
	v_cvt_pk_bf16_f32 v59, v62, v63
	global_store_dwordx4 v8, v[56:59], s[14:15]
	s_add_u32 s14, s14, 0x200000
	s_addc_u32 s15, s15, 0
	v_fma_f32 v64, v64, v80, v96
	v_fma_f32 v65, v65, v81, v97
	v_fma_f32 v66, v66, v82, v98
	v_fma_f32 v67, v67, v83, v99
	v_fma_f32 v68, v68, v84, v100
	v_fma_f32 v69, v69, v85, v101
	v_fma_f32 v70, v70, v86, v102
	v_fma_f32 v71, v71, v87, v103
	v_cvt_pk_bf16_f32 v64, v64, v65
	v_cvt_pk_bf16_f32 v65, v66, v67
	v_cvt_pk_bf16_f32 v66, v68, v69
	v_cvt_pk_bf16_f32 v67, v70, v71
	global_store_dwordx4 v8, v[64:67], s[14:15]
	s_add_u32 s14, s14, 0x200000
	s_addc_u32 s15, s15, 0
	global_load_dwordx4 v[72:75], v6, s[12:13]
	global_load_dwordx4 v[76:79], v6, s[12:13] offset:16
	global_load_dwordx4 v[88:91], v6, s[10:11]
	global_load_dwordx4 v[92:95], v6, s[10:11] offset:16
	global_load_dwordx4 v[40:43], v7, s[6:7]
	global_load_dwordx4 v[44:47], v7, s[6:7] offset:16
	s_add_u32 s6, s6, 0x400000
	s_addc_u32 s7, s7, 0
	global_load_dwordx4 v[48:51], v7, s[6:7]
	global_load_dwordx4 v[52:55], v7, s[6:7] offset:16
	s_add_u32 s6, s6, 0x400000
	s_addc_u32 s7, s7, 0
	s_add_u32 s12, s12, 0x6000
	s_addc_u32 s13, s13, 0
	s_add_u32 s10, s10, 0x6000
	s_addc_u32 s11, s11, 0
	s_nop 1
	global_load_dwordx4 v[80:83], v6, s[12:13]
	global_load_dwordx4 v[84:87], v6, s[12:13] offset:16
	global_load_dwordx4 v[96:99], v6, s[10:11]
	global_load_dwordx4 v[100:103], v6, s[10:11] offset:16
	global_load_dwordx4 v[56:59], v7, s[6:7]
	global_load_dwordx4 v[60:63], v7, s[6:7] offset:16
	s_add_u32 s6, s6, 0x400000
	s_addc_u32 s7, s7, 0
	global_load_dwordx4 v[64:67], v7, s[6:7]
	global_load_dwordx4 v[68:71], v7, s[6:7] offset:16
	s_add_u32 s6, s6, 0x400000
	s_addc_u32 s7, s7, 0
	s_add_u32 s12, s12, 0x6000
	s_addc_u32 s13, s13, 0
	s_add_u32 s10, s10, 0x6000
	s_addc_u32 s11, s11, 0
	s_nop 1
	s_waitcnt vmcnt(20)
	v_add_f32_e32 v136, 1.0, v136
	v_add_f32_e32 v137, 1.0, v137
	v_add_f32_e32 v138, 1.0, v138
	v_add_f32_e32 v139, 1.0, v139
	v_add_f32_e32 v140, 1.0, v140
	v_add_f32_e32 v141, 1.0, v141
	v_add_f32_e32 v142, 1.0, v142
	v_add_f32_e32 v143, 1.0, v143
	v_fma_f32 v104, v104, v136, v152
	v_fma_f32 v105, v105, v137, v153
	v_fma_f32 v106, v106, v138, v154
	v_fma_f32 v107, v107, v139, v155
	v_fma_f32 v108, v108, v140, v156
	v_fma_f32 v109, v109, v141, v157
	v_fma_f32 v110, v110, v142, v158
	v_fma_f32 v111, v111, v143, v159
	v_cvt_pk_bf16_f32 v104, v104, v105
	v_cvt_pk_bf16_f32 v105, v106, v107
	v_cvt_pk_bf16_f32 v106, v108, v109
	v_cvt_pk_bf16_f32 v107, v110, v111
	global_store_dwordx4 v8, v[104:107], s[14:15]
	s_add_u32 s14, s14, 0x200000
	s_addc_u32 s15, s15, 0
	v_fma_f32 v112, v112, v136, v152
	v_fma_f32 v113, v113, v137, v153
	v_fma_f32 v114, v114, v138, v154
	v_fma_f32 v115, v115, v139, v155
	v_fma_f32 v116, v116, v140, v156
	v_fma_f32 v117, v117, v141, v157
	v_fma_f32 v118, v118, v142, v158
	v_fma_f32 v119, v119, v143, v159
	v_cvt_pk_bf16_f32 v112, v112, v113
	v_cvt_pk_bf16_f32 v113, v114, v115
	v_cvt_pk_bf16_f32 v114, v116, v117
	v_cvt_pk_bf16_f32 v115, v118, v119
	global_store_dwordx4 v8, v[112:115], s[14:15]
	s_add_u32 s14, s14, 0x200000
	s_addc_u32 s15, s15, 0
	v_add_f32_e32 v144, 1.0, v144
	v_add_f32_e32 v145, 1.0, v145
	v_add_f32_e32 v146, 1.0, v146
	v_add_f32_e32 v147, 1.0, v147
	v_add_f32_e32 v148, 1.0, v148
	v_add_f32_e32 v149, 1.0, v149
	v_add_f32_e32 v150, 1.0, v150
	v_add_f32_e32 v151, 1.0, v151
	v_fma_f32 v120, v120, v144, v160
	v_fma_f32 v121, v121, v145, v161
	v_fma_f32 v122, v122, v146, v162
	v_fma_f32 v123, v123, v147, v163
	v_fma_f32 v124, v124, v148, v164
	v_fma_f32 v125, v125, v149, v165
	v_fma_f32 v126, v126, v150, v166
	v_fma_f32 v127, v127, v151, v167
	v_cvt_pk_bf16_f32 v120, v120, v121
	v_cvt_pk_bf16_f32 v121, v122, v123
	v_cvt_pk_bf16_f32 v122, v124, v125
	v_cvt_pk_bf16_f32 v123, v126, v127
	global_store_dwordx4 v8, v[120:123], s[14:15]
	s_add_u32 s14, s14, 0x200000
	s_addc_u32 s15, s15, 0
	v_fma_f32 v128, v128, v144, v160
; __device__ __forceinline__ unsigned pk2(float lo, float hi) { unsigned r; asm volatile("v_cvt_pk_bf16_f32 %0, %1, %2" : "=v"(r) : "v"(lo), "v"(hi)); return r; }
; __device__ __forceinline__ void modulate_phase(const float* X, const float* sh, const float* sc, bf16_t* H, int gtid, int gthreads) {
;     for (int idx = gtid; idx < T * 128; idx += gthreads) {
;         const int row = idx >> 7, c = (idx & 127) * 8, b = row >> 11;
;         const f32x4 x0 = *(const f32x4*)(X + (size_t)row * D + c), x1 = *(const f32x4*)(X + (size_t)row * D + c + 4);
;         const f32x4 s0 = *(const f32x4*)(sc + b * 6144 + c), s1 = *(const f32x4*)(sc + b * 6144 + c + 4);
;         const f32x4 h0 = *(const f32x4*)(sh + b * 6144 + c), h1 = *(const f32x4*)(sh + b * 6144 + c + 4);
;         const f32x4 v0 = x0 * (s0 + 1.f) + h0, v1 = x1 * (s1 + 1.f) + h1;
;         u32x4 w; w.x = pk2(v0[0], v0[1]); w.y = pk2(v0[2], v0[3]); w.z = pk2(v1[0], v1[1]); w.w = pk2(v1[2], v1[3]);
;         *(u32x4*)(H + (size_t)row * D + c) = w;
	v_fma_f32 v129, v129, v145, v161
	v_fma_f32 v130, v130, v146, v162
	v_fma_f32 v131, v131, v147, v163
	v_fma_f32 v132, v132, v148, v164
	v_fma_f32 v133, v133, v149, v165
	v_fma_f32 v134, v134, v150, v166
	v_fma_f32 v135, v135, v151, v167
	v_cvt_pk_bf16_f32 v128, v128, v129
	v_cvt_pk_bf16_f32 v129, v130, v131
	v_cvt_pk_bf16_f32 v130, v132, v133
	v_cvt_pk_bf16_f32 v131, v134, v135
	global_store_dwordx4 v8, v[128:131], s[14:15]
	s_add_u32 s14, s14, 0x200000
	s_addc_u32 s15, s15, 0
	global_load_dwordx4 v[136:139], v6, s[12:13]
	global_load_dwordx4 v[140:143], v6, s[12:13] offset:16
	global_load_dwordx4 v[152:155], v6, s[10:11]
	global_load_dwordx4 v[156:159], v6, s[10:11] offset:16
	global_load_dwordx4 v[104:107], v7, s[6:7]
	global_load_dwordx4 v[108:111], v7, s[6:7] offset:16
	s_add_u32 s6, s6, 0x400000
	s_addc_u32 s7, s7, 0
	global_load_dwordx4 v[112:115], v7, s[6:7]
	global_load_dwordx4 v[116:119], v7, s[6:7] offset:16
	s_add_u32 s6, s6, 0x400000
	s_addc_u32 s7, s7, 0
	s_add_u32 s12, s12, 0x6000
	s_addc_u32 s13, s13, 0
	s_add_u32 s10, s10, 0x6000
	s_addc_u32 s11, s11, 0
	s_nop 1
	global_load_dwordx4 v[144:147], v6, s[12:13]
	global_load_dwordx4 v[148:151], v6, s[12:13] offset:16
	global_load_dwordx4 v[160:163], v6, s[10:11]
	global_load_dwordx4 v[164:167], v6, s[10:11] offset:16
	global_load_dwordx4 v[120:123], v7, s[6:7]
	global_load_dwordx4 v[124:127], v7, s[6:7] offset:16
	s_add_u32 s6, s6, 0x400000
	s_addc_u32 s7, s7, 0
	global_load_dwordx4 v[128:131], v7, s[6:7]
	global_load_dwordx4 v[132:135], v7, s[6:7] offset:16
	s_add_u32 s6, s6, 0x400000
	s_addc_u32 s7, s7, 0
	s_add_u32 s12, s12, 0x6000
	s_addc_u32 s13, s13, 0
	s_add_u32 s10, s10, 0x6000
	s_addc_u32 s11, s11, 0
	s_nop 1
	s_waitcnt vmcnt(20)
	v_add_f32_e32 v72, 1.0, v72
	v_add_f32_e32 v73, 1.0, v73
	v_add_f32_e32 v74, 1.0, v74
	v_add_f32_e32 v75, 1.0, v75
	v_add_f32_e32 v76, 1.0, v76
	v_add_f32_e32 v77, 1.0, v77
	v_add_f32_e32 v78, 1.0, v78
	v_add_f32_e32 v79, 1.0, v79
	v_fma_f32 v40, v40, v72, v88
	v_fma_f32 v41, v41, v73, v89
	v_fma_f32 v42, v42, v74, v90
	v_fma_f32 v43, v43, v75, v91
	v_fma_f32 v44, v44, v76, v92
	v_fma_f32 v45, v45, v77, v93
	v_fma_f32 v46, v46, v78, v94
	v_fma_f32 v47, v47, v79, v95
	v_cvt_pk_bf16_f32 v40, v40, v41
	v_cvt_pk_bf16_f32 v41, v42, v43
	v_cvt_pk_bf16_f32 v42, v44, v45
	v_cvt_pk_bf16_f32 v43, v46, v47
	global_store_dwordx4 v8, v[40:43], s[14:15]
	s_add_u32 s14, s14, 0x200000
	s_addc_u32 s15, s15, 0
	v_fma_f32 v48, v48, v72, v88
	v_fma_f32 v49, v49, v73, v89
	v_fma_f32 v50, v50, v74, v90
	v_fma_f32 v51, v51, v75, v91
	v_fma_f32 v52, v52, v76, v92
	v_fma_f32 v53, v53, v77, v93
	v_fma_f32 v54, v54, v78, v94
	v_fma_f32 v55, v55, v79, v95
	v_cvt_pk_bf16_f32 v48, v48, v49
	v_cvt_pk_bf16_f32 v49, v50, v51
	v_cvt_pk_bf16_f32 v50, v52, v53
	v_cvt_pk_bf16_f32 v51, v54, v55
	global_store_dwordx4 v8, v[48:51], s[14:15]
	s_add_u32 s14, s14, 0x200000
	s_addc_u32 s15, s15, 0
	v_add_f32_e32 v80, 1.0, v80
	v_add_f32_e32 v81, 1.0, v81
	v_add_f32_e32 v82, 1.0, v82
	v_add_f32_e32 v83, 1.0, v83
	v_add_f32_e32 v84, 1.0, v84
	v_add_f32_e32 v85, 1.0, v85
	v_add_f32_e32 v86, 1.0, v86
	v_add_f32_e32 v87, 1.0, v87
	v_fma_f32 v56, v56, v80, v96
	v_fma_f32 v57, v57, v81, v97
	v_fma_f32 v58, v58, v82, v98
	v_fma_f32 v59, v59, v83, v99
	v_fma_f32 v60, v60, v84, v100
	v_fma_f32 v61, v61, v85, v101
	v_fma_f32 v62, v62, v86, v102
	v_fma_f32 v63, v63, v87, v103
	v_cvt_pk_bf16_f32 v56, v56, v57
	v_cvt_pk_bf16_f32 v57, v58, v59
	v_cvt_pk_bf16_f32 v58, v60, v61
	v_cvt_pk_bf16_f32 v59, v62, v63
	global_store_dwordx4 v8, v[56:59], s[14:15]
	s_add_u32 s14, s14, 0x200000
	s_addc_u32 s15, s15, 0
	v_fma_f32 v64, v64, v80, v96
	v_fma_f32 v65, v65, v81, v97
	v_fma_f32 v66, v66, v82, v98
	v_fma_f32 v67, v67, v83, v99
	v_fma_f32 v68, v68, v84, v100
	v_fma_f32 v69, v69, v85, v101
	v_fma_f32 v70, v70, v86, v102
	v_fma_f32 v71, v71, v87, v103
	v_cvt_pk_bf16_f32 v64, v64, v65
	v_cvt_pk_bf16_f32 v65, v66, v67
	v_cvt_pk_bf16_f32 v66, v68, v69
	v_cvt_pk_bf16_f32 v67, v70, v71
	global_store_dwordx4 v8, v[64:67], s[14:15]
	s_add_u32 s14, s14, 0x200000
	s_addc_u32 s15, s15, 0
	global_load_dwordx4 v[72:75], v6, s[12:13]
	global_load_dwordx4 v[76:79], v6, s[12:13] offset:16
	global_load_dwordx4 v[88:91], v6, s[10:11]
	global_load_dwordx4 v[92:95], v6, s[10:11] offset:16
	global_load_dwordx4 v[40:43], v7, s[6:7]
	global_load_dwordx4 v[44:47], v7, s[6:7] offset:16
	s_add_u32 s6, s6, 0x400000
	s_addc_u32 s7, s7, 0
	global_load_dwordx4 v[48:51], v7, s[6:7]
	global_load_dwordx4 v[52:55], v7, s[6:7] offset:16
	s_add_u32 s6, s6, 0x400000
	s_addc_u32 s7, s7, 0
	s_add_u32 s12, s12, 0x6000
	s_addc_u32 s13, s13, 0
	s_add_u32 s10, s10, 0x6000
	s_addc_u32 s11, s11, 0
	s_nop 1
	global_load_dwordx4 v[80:83], v6, s[12:13]
	global_load_dwordx4 v[84:87], v6, s[12:13] offset:16
	global_load_dwordx4 v[96:99], v6, s[10:11]
	global_load_dwordx4 v[100:103], v6, s[10:11] offset:16
	global_load_dwordx4 v[56:59], v7, s[6:7]
	global_load_dwordx4 v[60:63], v7, s[6:7] offset:16
	s_add_u32 s6, s6, 0x400000
	s_addc_u32 s7, s7, 0
	global_load_dwordx4 v[64:67], v7, s[6:7]
	global_load_dwordx4 v[68:71], v7, s[6:7] offset:16
	s_add_u32 s6, s6, 0x400000
	s_addc_u32 s7, s7, 0
	s_add_u32 s12, s12, 0x6000
	s_addc_u32 s13, s13, 0
	s_add_u32 s10, s10, 0x6000
	s_addc_u32 s11, s11, 0
	s_nop 1
	s_waitcnt vmcnt(20)
; __device__ __forceinline__ unsigned pk2(float lo, float hi) { unsigned r; asm volatile("v_cvt_pk_bf16_f32 %0, %1, %2" : "=v"(r) : "v"(lo), "v"(hi)); return r; }
; __device__ __forceinline__ void modulate_phase(const float* X, const float* sh, const float* sc, bf16_t* H, int gtid, int gthreads) {
;     for (int idx = gtid; idx < T * 128; idx += gthreads) {
;         const int row = idx >> 7, c = (idx & 127) * 8, b = row >> 11;
;         const f32x4 x0 = *(const f32x4*)(X + (size_t)row * D + c), x1 = *(const f32x4*)(X + (size_t)row * D + c + 4);
;         const f32x4 s0 = *(const f32x4*)(sc + b * 6144 + c), s1 = *(const f32x4*)(sc + b * 6144 + c + 4);
;         const f32x4 h0 = *(const f32x4*)(sh + b * 6144 + c), h1 = *(const f32x4*)(sh + b * 6144 + c + 4);
;         const f32x4 v0 = x0 * (s0 + 1.f) + h0, v1 = x1 * (s1 + 1.f) + h1;
;         u32x4 w; w.x = pk2(v0[0], v0[1]); w.y = pk2(v0[2], v0[3]); w.z = pk2(v1[0], v1[1]); w.w = pk2(v1[2], v1[3]);
;         *(u32x4*)(H + (size_t)row * D + c) = w;
	v_add_f32_e32 v136, 1.0, v136
	v_add_f32_e32 v137, 1.0, v137
	v_add_f32_e32 v138, 1.0, v138
	v_add_f32_e32 v139, 1.0, v139
	v_add_f32_e32 v140, 1.0, v140
	v_add_f32_e32 v141, 1.0, v141
	v_add_f32_e32 v142, 1.0, v142
	v_add_f32_e32 v143, 1.0, v143
	v_fma_f32 v104, v104, v136, v152
	v_fma_f32 v105, v105, v137, v153
	v_fma_f32 v106, v106, v138, v154
	v_fma_f32 v107, v107, v139, v155
	v_fma_f32 v108, v108, v140, v156
	v_fma_f32 v109, v109, v141, v157
	v_fma_f32 v110, v110, v142, v158
	v_fma_f32 v111, v111, v143, v159
	v_cvt_pk_bf16_f32 v104, v104, v105
	v_cvt_pk_bf16_f32 v105, v106, v107
	v_cvt_pk_bf16_f32 v106, v108, v109
	v_cvt_pk_bf16_f32 v107, v110, v111
	global_store_dwordx4 v8, v[104:107], s[14:15]
	s_add_u32 s14, s14, 0x200000
	s_addc_u32 s15, s15, 0
	v_fma_f32 v112, v112, v136, v152
	v_fma_f32 v113, v113, v137, v153
	v_fma_f32 v114, v114, v138, v154
	v_fma_f32 v115, v115, v139, v155
	v_fma_f32 v116, v116, v140, v156
	v_fma_f32 v117, v117, v141, v157
	v_fma_f32 v118, v118, v142, v158
	v_fma_f32 v119, v119, v143, v159
	v_cvt_pk_bf16_f32 v112, v112, v113
	v_cvt_pk_bf16_f32 v113, v114, v115
	v_cvt_pk_bf16_f32 v114, v116, v117
	v_cvt_pk_bf16_f32 v115, v118, v119
	global_store_dwordx4 v8, v[112:115], s[14:15]
	s_add_u32 s14, s14, 0x200000
	s_addc_u32 s15, s15, 0
	v_add_f32_e32 v144, 1.0, v144
	v_add_f32_e32 v145, 1.0, v145
	v_add_f32_e32 v146, 1.0, v146
	v_add_f32_e32 v147, 1.0, v147
	v_add_f32_e32 v148, 1.0, v148
	v_add_f32_e32 v149, 1.0, v149
	v_add_f32_e32 v150, 1.0, v150
	v_add_f32_e32 v151, 1.0, v151
	v_fma_f32 v120, v120, v144, v160
	v_fma_f32 v121, v121, v145, v161
	v_fma_f32 v122, v122, v146, v162
	v_fma_f32 v123, v123, v147, v163
	v_fma_f32 v124, v124, v148, v164
	v_fma_f32 v125, v125, v149, v165
	v_fma_f32 v126, v126, v150, v166
	v_fma_f32 v127, v127, v151, v167
	v_cvt_pk_bf16_f32 v120, v120, v121
	v_cvt_pk_bf16_f32 v121, v122, v123
	v_cvt_pk_bf16_f32 v122, v124, v125
	v_cvt_pk_bf16_f32 v123, v126, v127
	global_store_dwordx4 v8, v[120:123], s[14:15]
	s_add_u32 s14, s14, 0x200000
	s_addc_u32 s15, s15, 0
	v_fma_f32 v128, v128, v144, v160
	v_fma_f32 v129, v129, v145, v161
	v_fma_f32 v130, v130, v146, v162
	v_fma_f32 v131, v131, v147, v163
	v_fma_f32 v132, v132, v148, v164
	v_fma_f32 v133, v133, v149, v165
	v_fma_f32 v134, v134, v150, v166
	v_fma_f32 v135, v135, v151, v167
	v_cvt_pk_bf16_f32 v128, v128, v129
	v_cvt_pk_bf16_f32 v129, v130, v131
	v_cvt_pk_bf16_f32 v130, v132, v133
	v_cvt_pk_bf16_f32 v131, v134, v135
	global_store_dwordx4 v8, v[128:131], s[14:15]
	s_add_u32 s14, s14, 0x200000
	s_addc_u32 s15, s15, 0
	global_load_dwordx4 v[136:139], v6, s[12:13]
	global_load_dwordx4 v[140:143], v6, s[12:13] offset:16
	global_load_dwordx4 v[152:155], v6, s[10:11]
	global_load_dwordx4 v[156:159], v6, s[10:11] offset:16
	global_load_dwordx4 v[104:107], v7, s[6:7]
	global_load_dwordx4 v[108:111], v7, s[6:7] offset:16
	s_add_u32 s6, s6, 0x400000
	s_addc_u32 s7, s7, 0
	global_load_dwordx4 v[112:115], v7, s[6:7]
	global_load_dwordx4 v[116:119], v7, s[6:7] offset:16
	s_add_u32 s6, s6, 0x400000
	s_addc_u32 s7, s7, 0
	s_add_u32 s12, s12, 0x6000
	s_addc_u32 s13, s13, 0
	s_add_u32 s10, s10, 0x6000
	s_addc_u32 s11, s11, 0
	s_nop 1
	global_load_dwordx4 v[144:147], v6, s[12:13]
	global_load_dwordx4 v[148:151], v6, s[12:13] offset:16
	global_load_dwordx4 v[160:163], v6, s[10:11]
	global_load_dwordx4 v[164:167], v6, s[10:11] offset:16
	global_load_dwordx4 v[120:123], v7, s[6:7]
	global_load_dwordx4 v[124:127], v7, s[6:7] offset:16
	s_add_u32 s6, s6, 0x400000
	s_addc_u32 s7, s7, 0
	global_load_dwordx4 v[128:131], v7, s[6:7]
	global_load_dwordx4 v[132:135], v7, s[6:7] offset:16
	s_add_u32 s6, s6, 0x400000
	s_addc_u32 s7, s7, 0
	s_add_u32 s12, s12, 0x6000
	s_addc_u32 s13, s13, 0
	s_add_u32 s10, s10, 0x6000
	s_addc_u32 s11, s11, 0
	s_nop 1
	s_waitcnt vmcnt(20)
	v_add_f32_e32 v72, 1.0, v72
	v_add_f32_e32 v73, 1.0, v73
	v_add_f32_e32 v74, 1.0, v74
	v_add_f32_e32 v75, 1.0, v75
	v_add_f32_e32 v76, 1.0, v76
	v_add_f32_e32 v77, 1.0, v77
	v_add_f32_e32 v78, 1.0, v78
	v_add_f32_e32 v79, 1.0, v79
	v_fma_f32 v40, v40, v72, v88
	v_fma_f32 v41, v41, v73, v89
	v_fma_f32 v42, v42, v74, v90
	v_fma_f32 v43, v43, v75, v91
	v_fma_f32 v44, v44, v76, v92
	v_fma_f32 v45, v45, v77, v93
	v_fma_f32 v46, v46, v78, v94
	v_fma_f32 v47, v47, v79, v95
	v_cvt_pk_bf16_f32 v40, v40, v41
	v_cvt_pk_bf16_f32 v41, v42, v43
	v_cvt_pk_bf16_f32 v42, v44, v45
	v_cvt_pk_bf16_f32 v43, v46, v47
	global_store_dwordx4 v8, v[40:43], s[14:15]
	s_add_u32 s14, s14, 0x200000
	s_addc_u32 s15, s15, 0
	v_fma_f32 v48, v48, v72, v88
	v_fma_f32 v49, v49, v73, v89
	v_fma_f32 v50, v50, v74, v90
	v_fma_f32 v51, v51, v75, v91
	v_fma_f32 v52, v52, v76, v92
	v_fma_f32 v53, v53, v77, v93
	v_fma_f32 v54, v54, v78, v94
	v_fma_f32 v55, v55, v79, v95
	v_cvt_pk_bf16_f32 v48, v48, v49
	v_cvt_pk_bf16_f32 v49, v50, v51
	v_cvt_pk_bf16_f32 v50, v52, v53
	v_cvt_pk_bf16_f32 v51, v54, v55
	global_store_dwordx4 v8, v[48:51], s[14:15]
	s_add_u32 s14, s14, 0x200000
	s_addc_u32 s15, s15, 0
	v_add_f32_e32 v80, 1.0, v80
	v_add_f32_e32 v81, 1.0, v81
	v_add_f32_e32 v82, 1.0, v82
	v_add_f32_e32 v83, 1.0, v83
	v_add_f32_e32 v84, 1.0, v84
	v_add_f32_e32 v85, 1.0, v85
	v_add_f32_e32 v86, 1.0, v86
	v_add_f32_e32 v87, 1.0, v87
	v_fma_f32 v56, v56, v80, v96
	v_fma_f32 v57, v57, v81, v97
	v_fma_f32 v58, v58, v82, v98
	v_fma_f32 v59, v59, v83, v99
	v_fma_f32 v60, v60, v84, v100
	v_fma_f32 v61, v61, v85, v101
	v_fma_f32 v62, v62, v86, v102
	v_fma_f32 v63, v63, v87, v103
	v_cvt_pk_bf16_f32 v56, v56, v57
	v_cvt_pk_bf16_f32 v57, v58, v59
	v_cvt_pk_bf16_f32 v58, v60, v61
	v_cvt_pk_bf16_f32 v59, v62, v63
	global_store_dwordx4 v8, v[56:59], s[14:15]
; __device__ __forceinline__ unsigned pk2(float lo, float hi) { unsigned r; asm volatile("v_cvt_pk_bf16_f32 %0, %1, %2" : "=v"(r) : "v"(lo), "v"(hi)); return r; }
; __device__ __forceinline__ void modulate_phase(const float* X, const float* sh, const float* sc, bf16_t* H, int gtid, int gthreads) {
;     for (int idx = gtid; idx < T * 128; idx += gthreads) {
;         const int row = idx >> 7, c = (idx & 127) * 8, b = row >> 11;
;         const f32x4 x0 = *(const f32x4*)(X + (size_t)row * D + c), x1 = *(const f32x4*)(X + (size_t)row * D + c + 4);
;         const f32x4 s0 = *(const f32x4*)(sc + b * 6144 + c), s1 = *(const f32x4*)(sc + b * 6144 + c + 4);
;         const f32x4 h0 = *(const f32x4*)(sh + b * 6144 + c), h1 = *(const f32x4*)(sh + b * 6144 + c + 4);
;         const f32x4 v0 = x0 * (s0 + 1.f) + h0, v1 = x1 * (s1 + 1.f) + h1;
;         u32x4 w; w.x = pk2(v0[0], v0[1]); w.y = pk2(v0[2], v0[3]); w.z = pk2(v1[0], v1[1]); w.w = pk2(v1[2], v1[3]);
;         *(u32x4*)(H + (size_t)row * D + c) = w;
	s_add_u32 s14, s14, 0x200000
	s_addc_u32 s15, s15, 0
	v_fma_f32 v64, v64, v80, v96
	v_fma_f32 v65, v65, v81, v97
	v_fma_f32 v66, v66, v82, v98
	v_fma_f32 v67, v67, v83, v99
	v_fma_f32 v68, v68, v84, v100
	v_fma_f32 v69, v69, v85, v101
	v_fma_f32 v70, v70, v86, v102
	v_fma_f32 v71, v71, v87, v103
	v_cvt_pk_bf16_f32 v64, v64, v65
	v_cvt_pk_bf16_f32 v65, v66, v67
	v_cvt_pk_bf16_f32 v66, v68, v69
	v_cvt_pk_bf16_f32 v67, v70, v71
	global_store_dwordx4 v8, v[64:67], s[14:15]
	s_add_u32 s14, s14, 0x200000
	s_addc_u32 s15, s15, 0
	global_load_dwordx4 v[72:75], v6, s[12:13]
	global_load_dwordx4 v[76:79], v6, s[12:13] offset:16
	global_load_dwordx4 v[88:91], v6, s[10:11]
	global_load_dwordx4 v[92:95], v6, s[10:11] offset:16
	global_load_dwordx4 v[40:43], v7, s[6:7]
	global_load_dwordx4 v[44:47], v7, s[6:7] offset:16
	s_add_u32 s6, s6, 0x400000
	s_addc_u32 s7, s7, 0
	global_load_dwordx4 v[48:51], v7, s[6:7]
	global_load_dwordx4 v[52:55], v7, s[6:7] offset:16
	s_add_u32 s6, s6, 0x400000
	s_addc_u32 s7, s7, 0
	s_add_u32 s12, s12, 0x6000
	s_addc_u32 s13, s13, 0
	s_add_u32 s10, s10, 0x6000
	s_addc_u32 s11, s11, 0
	s_nop 1
	global_load_dwordx4 v[80:83], v6, s[12:13]
	global_load_dwordx4 v[84:87], v6, s[12:13] offset:16
	global_load_dwordx4 v[96:99], v6, s[10:11]
	global_load_dwordx4 v[100:103], v6, s[10:11] offset:16
	global_load_dwordx4 v[56:59], v7, s[6:7]
	global_load_dwordx4 v[60:63], v7, s[6:7] offset:16
	s_add_u32 s6, s6, 0x400000
	s_addc_u32 s7, s7, 0
	global_load_dwordx4 v[64:67], v7, s[6:7]
	global_load_dwordx4 v[68:71], v7, s[6:7] offset:16
	s_add_u32 s6, s6, 0x400000
	s_addc_u32 s7, s7, 0
	s_add_u32 s12, s12, 0x6000
	s_addc_u32 s13, s13, 0
	s_add_u32 s10, s10, 0x6000
	s_addc_u32 s11, s11, 0
	s_nop 1
	s_waitcnt vmcnt(20)
	v_add_f32_e32 v136, 1.0, v136
	v_add_f32_e32 v137, 1.0, v137
	v_add_f32_e32 v138, 1.0, v138
	v_add_f32_e32 v139, 1.0, v139
	v_add_f32_e32 v140, 1.0, v140
	v_add_f32_e32 v141, 1.0, v141
	v_add_f32_e32 v142, 1.0, v142
	v_add_f32_e32 v143, 1.0, v143
	v_fma_f32 v104, v104, v136, v152
	v_fma_f32 v105, v105, v137, v153
	v_fma_f32 v106, v106, v138, v154
	v_fma_f32 v107, v107, v139, v155
	v_fma_f32 v108, v108, v140, v156
	v_fma_f32 v109, v109, v141, v157
	v_fma_f32 v110, v110, v142, v158
	v_fma_f32 v111, v111, v143, v159
	v_cvt_pk_bf16_f32 v104, v104, v105
	v_cvt_pk_bf16_f32 v105, v106, v107
	v_cvt_pk_bf16_f32 v106, v108, v109
	v_cvt_pk_bf16_f32 v107, v110, v111
	global_store_dwordx4 v8, v[104:107], s[14:15]
	s_add_u32 s14, s14, 0x200000
	s_addc_u32 s15, s15, 0
	v_fma_f32 v112, v112, v136, v152
	v_fma_f32 v113, v113, v137, v153
	v_fma_f32 v114, v114, v138, v154
	v_fma_f32 v115, v115, v139, v155
	v_fma_f32 v116, v116, v140, v156
	v_fma_f32 v117, v117, v141, v157
	v_fma_f32 v118, v118, v142, v158
	v_fma_f32 v119, v119, v143, v159
	v_cvt_pk_bf16_f32 v112, v112, v113
	v_cvt_pk_bf16_f32 v113, v114, v115
	v_cvt_pk_bf16_f32 v114, v116, v117
	v_cvt_pk_bf16_f32 v115, v118, v119
	global_store_dwordx4 v8, v[112:115], s[14:15]
	s_add_u32 s14, s14, 0x200000
	s_addc_u32 s15, s15, 0
	v_add_f32_e32 v144, 1.0, v144
	v_add_f32_e32 v145, 1.0, v145
	v_add_f32_e32 v146, 1.0, v146
	v_add_f32_e32 v147, 1.0, v147
	v_add_f32_e32 v148, 1.0, v148
	v_add_f32_e32 v149, 1.0, v149
	v_add_f32_e32 v150, 1.0, v150
	v_add_f32_e32 v151, 1.0, v151
	v_fma_f32 v120, v120, v144, v160
	v_fma_f32 v121, v121, v145, v161
	v_fma_f32 v122, v122, v146, v162
	v_fma_f32 v123, v123, v147, v163
	v_fma_f32 v124, v124, v148, v164
	v_fma_f32 v125, v125, v149, v165
	v_fma_f32 v126, v126, v150, v166
	v_fma_f32 v127, v127, v151, v167
	v_cvt_pk_bf16_f32 v120, v120, v121
	v_cvt_pk_bf16_f32 v121, v122, v123
	v_cvt_pk_bf16_f32 v122, v124, v125
	v_cvt_pk_bf16_f32 v123, v126, v127
	global_store_dwordx4 v8, v[120:123], s[14:15]
	s_add_u32 s14, s14, 0x200000
	s_addc_u32 s15, s15, 0
	v_fma_f32 v128, v128, v144, v160
	v_fma_f32 v129, v129, v145, v161
	v_fma_f32 v130, v130, v146, v162
	v_fma_f32 v131, v131, v147, v163
	v_fma_f32 v132, v132, v148, v164
	v_fma_f32 v133, v133, v149, v165
	v_fma_f32 v134, v134, v150, v166
	v_fma_f32 v135, v135, v151, v167
	v_cvt_pk_bf16_f32 v128, v128, v129
	v_cvt_pk_bf16_f32 v129, v130, v131
	v_cvt_pk_bf16_f32 v130, v132, v133
	v_cvt_pk_bf16_f32 v131, v134, v135
	global_store_dwordx4 v8, v[128:131], s[14:15]
	s_add_u32 s14, s14, 0x200000
	s_addc_u32 s15, s15, 0
	global_load_dwordx4 v[136:139], v6, s[12:13]
	global_load_dwordx4 v[140:143], v6, s[12:13] offset:16
	global_load_dwordx4 v[152:155], v6, s[10:11]
	global_load_dwordx4 v[156:159], v6, s[10:11] offset:16
	global_load_dwordx4 v[104:107], v7, s[6:7]
	global_load_dwordx4 v[108:111], v7, s[6:7] offset:16
	s_add_u32 s6, s6, 0x400000
	s_addc_u32 s7, s7, 0
	global_load_dwordx4 v[112:115], v7, s[6:7]
	global_load_dwordx4 v[116:119], v7, s[6:7] offset:16
	s_add_u32 s6, s6, 0x400000
	s_addc_u32 s7, s7, 0
	s_add_u32 s12, s12, 0x6000
	s_addc_u32 s13, s13, 0
	s_add_u32 s10, s10, 0x6000
	s_addc_u32 s11, s11, 0
	s_nop 1
	global_load_dwordx4 v[144:147], v6, s[12:13]
	global_load_dwordx4 v[148:151], v6, s[12:13] offset:16
	global_load_dwordx4 v[160:163], v6, s[10:11]
	global_load_dwordx4 v[164:167], v6, s[10:11] offset:16
	global_load_dwordx4 v[120:123], v7, s[6:7]
	global_load_dwordx4 v[124:127], v7, s[6:7] offset:16
	s_add_u32 s6, s6, 0x400000
	s_addc_u32 s7, s7, 0
	global_load_dwordx4 v[128:131], v7, s[6:7]
	global_load_dwordx4 v[132:135], v7, s[6:7] offset:16
	s_add_u32 s6, s6, 0x400000
	s_addc_u32 s7, s7, 0
	s_add_u32 s12, s12, 0x6000
	s_addc_u32 s13, s13, 0
	s_add_u32 s10, s10, 0x6000
	s_addc_u32 s11, s11, 0
	s_nop 1
	s_waitcnt vmcnt(20)
; __device__ __forceinline__ unsigned pk2(float lo, float hi) { unsigned r; asm volatile("v_cvt_pk_bf16_f32 %0, %1, %2" : "=v"(r) : "v"(lo), "v"(hi)); return r; }
; __device__ __forceinline__ void modulate_phase(const float* X, const float* sh, const float* sc, bf16_t* H, int gtid, int gthreads) {
;     for (int idx = gtid; idx < T * 128; idx += gthreads) {
;         const int row = idx >> 7, c = (idx & 127) * 8, b = row >> 11;
;         const f32x4 x0 = *(const f32x4*)(X + (size_t)row * D + c), x1 = *(const f32x4*)(X + (size_t)row * D + c + 4);
;         const f32x4 s0 = *(const f32x4*)(sc + b * 6144 + c), s1 = *(const f32x4*)(sc + b * 6144 + c + 4);
;         const f32x4 h0 = *(const f32x4*)(sh + b * 6144 + c), h1 = *(const f32x4*)(sh + b * 6144 + c + 4);
;         const f32x4 v0 = x0 * (s0 + 1.f) + h0, v1 = x1 * (s1 + 1.f) + h1;
;         u32x4 w; w.x = pk2(v0[0], v0[1]); w.y = pk2(v0[2], v0[3]); w.z = pk2(v1[0], v1[1]); w.w = pk2(v1[2], v1[3]);
;         *(u32x4*)(H + (size_t)row * D + c) = w;
	v_add_f32_e32 v72, 1.0, v72
	v_add_f32_e32 v73, 1.0, v73
	v_add_f32_e32 v74, 1.0, v74
	v_add_f32_e32 v75, 1.0, v75
	v_add_f32_e32 v76, 1.0, v76
	v_add_f32_e32 v77, 1.0, v77
	v_add_f32_e32 v78, 1.0, v78
	v_add_f32_e32 v79, 1.0, v79
	v_fma_f32 v40, v40, v72, v88
	v_fma_f32 v41, v41, v73, v89
	v_fma_f32 v42, v42, v74, v90
	v_fma_f32 v43, v43, v75, v91
	v_fma_f32 v44, v44, v76, v92
	v_fma_f32 v45, v45, v77, v93
	v_fma_f32 v46, v46, v78, v94
	v_fma_f32 v47, v47, v79, v95
	v_cvt_pk_bf16_f32 v40, v40, v41
	v_cvt_pk_bf16_f32 v41, v42, v43
	v_cvt_pk_bf16_f32 v42, v44, v45
	v_cvt_pk_bf16_f32 v43, v46, v47
	global_store_dwordx4 v8, v[40:43], s[14:15]
	s_add_u32 s14, s14, 0x200000
	s_addc_u32 s15, s15, 0
	v_fma_f32 v48, v48, v72, v88
	v_fma_f32 v49, v49, v73, v89
	v_fma_f32 v50, v50, v74, v90
	v_fma_f32 v51, v51, v75, v91
	v_fma_f32 v52, v52, v76, v92
	v_fma_f32 v53, v53, v77, v93
	v_fma_f32 v54, v54, v78, v94
	v_fma_f32 v55, v55, v79, v95
	v_cvt_pk_bf16_f32 v48, v48, v49
	v_cvt_pk_bf16_f32 v49, v50, v51
	v_cvt_pk_bf16_f32 v50, v52, v53
	v_cvt_pk_bf16_f32 v51, v54, v55
	global_store_dwordx4 v8, v[48:51], s[14:15]
	s_add_u32 s14, s14, 0x200000
	s_addc_u32 s15, s15, 0
	v_add_f32_e32 v80, 1.0, v80
	v_add_f32_e32 v81, 1.0, v81
	v_add_f32_e32 v82, 1.0, v82
	v_add_f32_e32 v83, 1.0, v83
	v_add_f32_e32 v84, 1.0, v84
	v_add_f32_e32 v85, 1.0, v85
	v_add_f32_e32 v86, 1.0, v86
	v_add_f32_e32 v87, 1.0, v87
	v_fma_f32 v56, v56, v80, v96
	v_fma_f32 v57, v57, v81, v97
	v_fma_f32 v58, v58, v82, v98
	v_fma_f32 v59, v59, v83, v99
	v_fma_f32 v60, v60, v84, v100
	v_fma_f32 v61, v61, v85, v101
	v_fma_f32 v62, v62, v86, v102
	v_fma_f32 v63, v63, v87, v103
	v_cvt_pk_bf16_f32 v56, v56, v57
	v_cvt_pk_bf16_f32 v57, v58, v59
	v_cvt_pk_bf16_f32 v58, v60, v61
	v_cvt_pk_bf16_f32 v59, v62, v63
	global_store_dwordx4 v8, v[56:59], s[14:15]
	s_add_u32 s14, s14, 0x200000
	s_addc_u32 s15, s15, 0
	v_fma_f32 v64, v64, v80, v96
	v_fma_f32 v65, v65, v81, v97
	v_fma_f32 v66, v66, v82, v98
	v_fma_f32 v67, v67, v83, v99
	v_fma_f32 v68, v68, v84, v100
	v_fma_f32 v69, v69, v85, v101
	v_fma_f32 v70, v70, v86, v102
	v_fma_f32 v71, v71, v87, v103
	v_cvt_pk_bf16_f32 v64, v64, v65
	v_cvt_pk_bf16_f32 v65, v66, v67
	v_cvt_pk_bf16_f32 v66, v68, v69
	v_cvt_pk_bf16_f32 v67, v70, v71
	global_store_dwordx4 v8, v[64:67], s[14:15]
	s_add_u32 s14, s14, 0x200000
	s_addc_u32 s15, s15, 0
	s_waitcnt vmcnt(4)
	v_add_f32_e32 v136, 1.0, v136
	v_add_f32_e32 v137, 1.0, v137
	v_add_f32_e32 v138, 1.0, v138
	v_add_f32_e32 v139, 1.0, v139
	v_add_f32_e32 v140, 1.0, v140
	v_add_f32_e32 v141, 1.0, v141
	v_add_f32_e32 v142, 1.0, v142
	v_add_f32_e32 v143, 1.0, v143
	v_fma_f32 v104, v104, v136, v152
	v_fma_f32 v105, v105, v137, v153
	v_fma_f32 v106, v106, v138, v154
	v_fma_f32 v107, v107, v139, v155
	v_fma_f32 v108, v108, v140, v156
	v_fma_f32 v109, v109, v141, v157
	v_fma_f32 v110, v110, v142, v158
	v_fma_f32 v111, v111, v143, v159
	v_cvt_pk_bf16_f32 v104, v104, v105
	v_cvt_pk_bf16_f32 v105, v106, v107
	v_cvt_pk_bf16_f32 v106, v108, v109
	v_cvt_pk_bf16_f32 v107, v110, v111
	global_store_dwordx4 v8, v[104:107], s[14:15]
	s_add_u32 s14, s14, 0x200000
	s_addc_u32 s15, s15, 0
	v_fma_f32 v112, v112, v136, v152
	v_fma_f32 v113, v113, v137, v153
	v_fma_f32 v114, v114, v138, v154
	v_fma_f32 v115, v115, v139, v155
	v_fma_f32 v116, v116, v140, v156
	v_fma_f32 v117, v117, v141, v157
	v_fma_f32 v118, v118, v142, v158
	v_fma_f32 v119, v119, v143, v159
	v_cvt_pk_bf16_f32 v112, v112, v113
	v_cvt_pk_bf16_f32 v113, v114, v115
	v_cvt_pk_bf16_f32 v114, v116, v117
	v_cvt_pk_bf16_f32 v115, v118, v119
	global_store_dwordx4 v8, v[112:115], s[14:15]
	s_add_u32 s14, s14, 0x200000
	s_addc_u32 s15, s15, 0
	v_add_f32_e32 v144, 1.0, v144
	v_add_f32_e32 v145, 1.0, v145
	v_add_f32_e32 v146, 1.0, v146
	v_add_f32_e32 v147, 1.0, v147
	v_add_f32_e32 v148, 1.0, v148
	v_add_f32_e32 v149, 1.0, v149
	v_add_f32_e32 v150, 1.0, v150
	v_add_f32_e32 v151, 1.0, v151
	v_fma_f32 v120, v120, v144, v160
	v_fma_f32 v121, v121, v145, v161
	v_fma_f32 v122, v122, v146, v162
	v_fma_f32 v123, v123, v147, v163
	v_fma_f32 v124, v124, v148, v164
	v_fma_f32 v125, v125, v149, v165
	v_fma_f32 v126, v126, v150, v166
	v_fma_f32 v127, v127, v151, v167
	v_cvt_pk_bf16_f32 v120, v120, v121
	v_cvt_pk_bf16_f32 v121, v122, v123
	v_cvt_pk_bf16_f32 v122, v124, v125
	v_cvt_pk_bf16_f32 v123, v126, v127
	global_store_dwordx4 v8, v[120:123], s[14:15]
	s_add_u32 s14, s14, 0x200000
	s_addc_u32 s15, s15, 0
	v_fma_f32 v128, v128, v144, v160
	v_fma_f32 v129, v129, v145, v161
	v_fma_f32 v130, v130, v146, v162
	v_fma_f32 v131, v131, v147, v163
	v_fma_f32 v132, v132, v148, v164
	v_fma_f32 v133, v133, v149, v165
	v_fma_f32 v134, v134, v150, v166
	v_fma_f32 v135, v135, v151, v167
	v_cvt_pk_bf16_f32 v128, v128, v129
	v_cvt_pk_bf16_f32 v129, v130, v131
	v_cvt_pk_bf16_f32 v130, v132, v133
	v_cvt_pk_bf16_f32 v131, v134, v135
	global_store_dwordx4 v8, v[128:131], s[14:15]
	s_add_u32 s14, s14, 0x200000
	s_addc_u32 s15, s15, 0
	s_branch .LBB0_61
